# v5 + 64-byte alignment of the six GEMM K-loop heads and the diff-attn main loop head
# speedup vs baseline: 1.0008x; 1.0007x over previous
.LBB0_159:
	s_ashr_i32 s5, s4, 31
	s_lshl_b64 s[10:11], s[4:5], 20
	s_add_u32 s10, s22, s10
	s_addc_u32 s11, s23, s11
	s_and_b64 s[12:13], s[8:9], exec
	s_cselect_b32 s5, s11, s17
	s_cselect_b32 s43, s10, s16
	s_ashr_i32 s7, s6, 31
	s_lshl_b64 s[12:13], s[6:7], 20
	s_add_u32 s12, s24, s12
	s_addc_u32 s13, s25, s13
	s_and_b64 s[18:19], s[8:9], exec
	s_cselect_b32 s7, s13, s15
	s_cselect_b32 s44, s12, s14
	s_add_u32 s45, s14, 0x10000
	s_addc_u32 s46, s15, 0
	s_add_u32 s14, s16, 0x80080
	s_addc_u32 s15, s17, 0
	s_mov_b32 s47, -2
	s_add_u32 s16, s14, 0xfff80080
	s_addc_u32 s17, s15, -1
	s_add_i32 s48, 0, 0x10000
	s_cmp_eq_u32 s47, 28
	s_cselect_b32 s19, s5, s17
	s_cselect_b32 s18, s43, s16
	s_cselect_b32 s17, s7, s46
	s_cselect_b32 s16, s44, s45
	s_add_i32 s50, 0, 0x14000
	v_add_u32_e32 v168, s48, v158
	v_add_u32_e32 v184, s50, v158
	ds_read_b128 v[154:157], v168
	ds_read_b128 v[160:163], v168 offset:1024
	ds_read_b128 v[164:167], v168 offset:2048
	ds_read_b128 v[168:171], v168 offset:3072
	ds_read_b128 v[172:175], v184
	ds_read_b128 v[176:179], v184 offset:1024
	ds_read_b128 v[180:183], v184 offset:2048
	ds_read_b128 v[184:187], v184 offset:3072
	v_lshl_add_u64 v[204:205], s[14:15], 0, v[150:151]
	s_add_i32 m0, s28, 0xc000
	ds_read_b128 v[188:191], v159
	ds_read_b128 v[192:195], v159 offset:1024
	ds_read_b128 v[196:199], v159 offset:2048
	ds_read_b128 v[200:203], v159 offset:3072
	ds_read_b128 v[214:217], v159 offset:4096
	ds_read_b128 v[218:221], v159 offset:5120
	ds_read_b128 v[222:225], v159 offset:6144
	ds_read_b128 v[226:229], v159 offset:7168
	global_load_lds_dwordx4 v[204:205], off
	v_lshl_add_u64 v[204:205], s[14:15], 0, v[152:153]
	s_add_i32 m0, s28, 0xe000
	s_nop 0
	global_load_lds_dwordx4 v[204:205], off
	s_waitcnt vmcnt(8)
	s_waitcnt lgkmcnt(0)
	s_barrier
	s_setprio 1
	s_waitcnt lgkmcnt(0)
	v_mfma_f32_16x16x32_bf16 v[128:131], v[154:157], v[188:191], 0
	v_mfma_f32_16x16x32_bf16 v[120:123], v[164:167], v[188:191], 0
	v_mfma_f32_16x16x32_bf16 v[112:115], v[154:157], v[196:199], 0
	v_mfma_f32_16x16x32_bf16 v[104:107], v[164:167], v[196:199], 0
	v_mfma_f32_16x16x32_bf16 v[96:99], v[154:157], v[214:217], 0
	v_mfma_f32_16x16x32_bf16 v[88:91], v[164:167], v[214:217], 0
	v_mfma_f32_16x16x32_bf16 v[80:83], v[154:157], v[222:225], 0
	v_mfma_f32_16x16x32_bf16 v[72:75], v[164:167], v[222:225], 0
	v_mfma_f32_16x16x32_bf16 v[128:131], v[160:163], v[192:195], v[128:131]
	v_mfma_f32_16x16x32_bf16 v[120:123], v[168:171], v[192:195], v[120:123]
	v_mfma_f32_16x16x32_bf16 v[112:115], v[160:163], v[200:203], v[112:115]
	v_mfma_f32_16x16x32_bf16 v[104:107], v[168:171], v[200:203], v[104:107]
	v_mfma_f32_16x16x32_bf16 v[96:99], v[160:163], v[218:221], v[96:99]
	v_mfma_f32_16x16x32_bf16 v[88:91], v[168:171], v[218:221], v[88:91]
	v_mfma_f32_16x16x32_bf16 v[80:83], v[160:163], v[226:229], v[80:83]
	v_mfma_f32_16x16x32_bf16 v[72:75], v[168:171], v[226:229], v[72:75]
	s_setprio 0
	s_setprio 1
	v_mfma_f32_16x16x32_bf16 v[124:127], v[172:175], v[188:191], 0
	v_mfma_f32_16x16x32_bf16 v[116:119], v[180:183], v[188:191], 0
	v_mfma_f32_16x16x32_bf16 v[108:111], v[172:175], v[196:199], 0
	v_mfma_f32_16x16x32_bf16 v[100:103], v[180:183], v[196:199], 0
	v_mfma_f32_16x16x32_bf16 v[92:95], v[172:175], v[214:217], 0
	v_mfma_f32_16x16x32_bf16 v[84:87], v[180:183], v[214:217], 0
	v_mfma_f32_16x16x32_bf16 v[76:79], v[172:175], v[222:225], 0
	v_mfma_f32_16x16x32_bf16 v[68:71], v[180:183], v[222:225], 0
	v_mfma_f32_16x16x32_bf16 v[124:127], v[176:179], v[192:195], v[124:127]
	v_mfma_f32_16x16x32_bf16 v[116:119], v[184:187], v[192:195], v[116:119]
	v_mfma_f32_16x16x32_bf16 v[108:111], v[176:179], v[200:203], v[108:111]
	v_mfma_f32_16x16x32_bf16 v[100:103], v[184:187], v[200:203], v[100:103]
	v_mfma_f32_16x16x32_bf16 v[92:95], v[176:179], v[218:221], v[92:95]
	v_mfma_f32_16x16x32_bf16 v[84:87], v[184:187], v[218:221], v[84:87]
	v_mfma_f32_16x16x32_bf16 v[76:79], v[176:179], v[226:229], v[76:79]
	v_mfma_f32_16x16x32_bf16 v[68:71], v[184:187], v[226:229], v[68:71]
	s_setprio 0
	s_barrier
	s_add_i32 s48, s48, s27
	v_lshl_add_u64 v[204:205], s[16:17], 0, v[136:137]
	s_mov_b32 m0, s48
	ds_read_b128 v[188:191], v159 offset:16384
	ds_read_b128 v[192:195], v159 offset:17408
	ds_read_b128 v[196:199], v159 offset:18432
	ds_read_b128 v[200:203], v159 offset:19456
	ds_read_b128 v[214:217], v159 offset:20480
	ds_read_b128 v[218:221], v159 offset:21504
	ds_read_b128 v[222:225], v159 offset:22528
	ds_read_b128 v[226:229], v159 offset:23552
	global_load_lds_dwordx4 v[204:205], off
	s_add_i32 m0, s48, 0x2000
	s_add_u32 s48, s16, 0x4000
	v_lshl_add_u64 v[204:205], s[16:17], 0, v[132:133]
	s_addc_u32 s49, s17, 0
	s_add_i32 s50, s50, s27
	global_load_lds_dwordx4 v[204:205], off
	v_lshl_add_u64 v[204:205], s[48:49], 0, v[136:137]
	s_mov_b32 m0, s50
	v_lshl_add_u64 v[206:207], s[18:19], 0, v[134:135]
	global_load_lds_dwordx4 v[204:205], off
	v_lshl_add_u64 v[204:205], s[48:49], 0, v[132:133]
	s_add_i32 m0, s50, 0x2000
	s_nop 0
	global_load_lds_dwordx4 v[204:205], off
	v_lshl_add_u64 v[204:205], s[18:19], 0, v[138:139]
	s_mov_b32 m0, s28
	s_nop 0
	global_load_lds_dwordx4 v[204:205], off
	s_mov_b32 m0, s29
	s_nop 0
	global_load_lds_dwordx4 v[206:207], off
	s_waitcnt vmcnt(8)
	s_waitcnt lgkmcnt(0)
	s_barrier
	s_setprio 1
	s_waitcnt lgkmcnt(0)
	v_mfma_f32_16x16x32_bf16 v[64:67], v[154:157], v[188:191], 0
	v_mfma_f32_16x16x32_bf16 v[56:59], v[164:167], v[188:191], 0
	v_mfma_f32_16x16x32_bf16 v[48:51], v[154:157], v[196:199], 0
	v_mfma_f32_16x16x32_bf16 v[40:43], v[164:167], v[196:199], 0
	v_mfma_f32_16x16x32_bf16 v[32:35], v[154:157], v[214:217], 0
	v_mfma_f32_16x16x32_bf16 v[24:27], v[164:167], v[214:217], 0
	v_mfma_f32_16x16x32_bf16 v[16:19], v[154:157], v[222:225], 0
	v_mfma_f32_16x16x32_bf16 v[8:11], v[164:167], v[222:225], 0
	v_mfma_f32_16x16x32_bf16 v[64:67], v[160:163], v[192:195], v[64:67]
	v_mfma_f32_16x16x32_bf16 v[56:59], v[168:171], v[192:195], v[56:59]
	v_mfma_f32_16x16x32_bf16 v[48:51], v[160:163], v[200:203], v[48:51]
	v_mfma_f32_16x16x32_bf16 v[40:43], v[168:171], v[200:203], v[40:43]
	v_mfma_f32_16x16x32_bf16 v[32:35], v[160:163], v[218:221], v[32:35]
	v_mfma_f32_16x16x32_bf16 v[24:27], v[168:171], v[218:221], v[24:27]
	v_mfma_f32_16x16x32_bf16 v[16:19], v[160:163], v[226:229], v[16:19]
	v_mfma_f32_16x16x32_bf16 v[8:11], v[168:171], v[226:229], v[8:11]
	s_setprio 0
	s_setprio 1
	v_mfma_f32_16x16x32_bf16 v[60:63], v[172:175], v[188:191], 0
	v_mfma_f32_16x16x32_bf16 v[52:55], v[180:183], v[188:191], 0
	v_mfma_f32_16x16x32_bf16 v[44:47], v[172:175], v[196:199], 0
	v_mfma_f32_16x16x32_bf16 v[36:39], v[180:183], v[196:199], 0
	v_mfma_f32_16x16x32_bf16 v[28:31], v[172:175], v[214:217], 0
	v_mfma_f32_16x16x32_bf16 v[20:23], v[180:183], v[214:217], 0
	v_mfma_f32_16x16x32_bf16 v[12:15], v[172:175], v[222:225], 0
	v_mfma_f32_16x16x32_bf16 v[4:7], v[180:183], v[222:225], 0
	v_mfma_f32_16x16x32_bf16 v[60:63], v[176:179], v[192:195], v[60:63]
	v_mfma_f32_16x16x32_bf16 v[52:55], v[184:187], v[192:195], v[52:55]
	v_mfma_f32_16x16x32_bf16 v[44:47], v[176:179], v[200:203], v[44:47]
	v_mfma_f32_16x16x32_bf16 v[36:39], v[184:187], v[200:203], v[36:39]
	v_mfma_f32_16x16x32_bf16 v[28:31], v[176:179], v[218:221], v[28:31]
	v_mfma_f32_16x16x32_bf16 v[20:23], v[184:187], v[218:221], v[20:23]
	v_mfma_f32_16x16x32_bf16 v[12:15], v[176:179], v[226:229], v[12:15]
	v_mfma_f32_16x16x32_bf16 v[4:7], v[184:187], v[226:229], v[4:7]
	s_setprio 0
	s_barrier
	s_add_i32 s48, 0, 0x18000
	s_add_i32 s49, 0, 0x1c000
	v_add_u32_e32 v168, s48, v158
	v_add_u32_e32 v184, s49, v158
	ds_read_b128 v[154:157], v168
	ds_read_b128 v[160:163], v168 offset:1024
	ds_read_b128 v[164:167], v168 offset:2048
	ds_read_b128 v[168:171], v168 offset:3072
	ds_read_b128 v[172:175], v184
	ds_read_b128 v[176:179], v184 offset:1024
	ds_read_b128 v[180:183], v184 offset:2048
	ds_read_b128 v[184:187], v184 offset:3072
	s_add_u32 s18, s18, 0x80000
	s_addc_u32 s19, s19, 0
	s_mov_b32 m0, s30
	v_lshl_add_u64 v[208:209], s[18:19], 0, v[138:139]
	ds_read_b128 v[188:191], v159 offset:32768
	ds_read_b128 v[192:195], v159 offset:33792
	ds_read_b128 v[196:199], v159 offset:34816
	ds_read_b128 v[200:203], v159 offset:35840
	ds_read_b128 v[214:217], v159 offset:36864
	ds_read_b128 v[218:221], v159 offset:37888
	ds_read_b128 v[222:225], v159 offset:38912
	ds_read_b128 v[226:229], v159 offset:39936
	global_load_lds_dwordx4 v[208:209], off
	v_lshl_add_u64 v[208:209], s[18:19], 0, v[134:135]
	s_mov_b32 m0, s31
	s_nop 0
	global_load_lds_dwordx4 v[208:209], off
	s_waitcnt vmcnt(8)
	s_waitcnt lgkmcnt(0)
	s_barrier
	s_setprio 1
	s_waitcnt lgkmcnt(0)
	v_mfma_f32_16x16x32_bf16 v[128:131], v[154:157], v[188:191], v[128:131]
	v_mfma_f32_16x16x32_bf16 v[120:123], v[164:167], v[188:191], v[120:123]
	v_mfma_f32_16x16x32_bf16 v[112:115], v[154:157], v[196:199], v[112:115]
	v_mfma_f32_16x16x32_bf16 v[104:107], v[164:167], v[196:199], v[104:107]
	v_mfma_f32_16x16x32_bf16 v[96:99], v[154:157], v[214:217], v[96:99]
	v_mfma_f32_16x16x32_bf16 v[88:91], v[164:167], v[214:217], v[88:91]
	v_mfma_f32_16x16x32_bf16 v[80:83], v[154:157], v[222:225], v[80:83]
	v_mfma_f32_16x16x32_bf16 v[72:75], v[164:167], v[222:225], v[72:75]
	v_mfma_f32_16x16x32_bf16 v[128:131], v[160:163], v[192:195], v[128:131]
	v_mfma_f32_16x16x32_bf16 v[120:123], v[168:171], v[192:195], v[120:123]
	v_mfma_f32_16x16x32_bf16 v[112:115], v[160:163], v[200:203], v[112:115]
	v_mfma_f32_16x16x32_bf16 v[104:107], v[168:171], v[200:203], v[104:107]
	v_mfma_f32_16x16x32_bf16 v[96:99], v[160:163], v[218:221], v[96:99]
	v_mfma_f32_16x16x32_bf16 v[88:91], v[168:171], v[218:221], v[88:91]
	v_mfma_f32_16x16x32_bf16 v[80:83], v[160:163], v[226:229], v[80:83]
	v_mfma_f32_16x16x32_bf16 v[72:75], v[168:171], v[226:229], v[72:75]
	s_setprio 0
	s_setprio 1
	v_mfma_f32_16x16x32_bf16 v[124:127], v[172:175], v[188:191], v[124:127]
	v_mfma_f32_16x16x32_bf16 v[116:119], v[180:183], v[188:191], v[116:119]
	v_mfma_f32_16x16x32_bf16 v[108:111], v[172:175], v[196:199], v[108:111]
	v_mfma_f32_16x16x32_bf16 v[100:103], v[180:183], v[196:199], v[100:103]
	v_mfma_f32_16x16x32_bf16 v[92:95], v[172:175], v[214:217], v[92:95]
	v_mfma_f32_16x16x32_bf16 v[84:87], v[180:183], v[214:217], v[84:87]
	v_mfma_f32_16x16x32_bf16 v[76:79], v[172:175], v[222:225], v[76:79]
	v_mfma_f32_16x16x32_bf16 v[68:71], v[180:183], v[222:225], v[68:71]
	v_mfma_f32_16x16x32_bf16 v[124:127], v[176:179], v[192:195], v[124:127]
	v_mfma_f32_16x16x32_bf16 v[116:119], v[184:187], v[192:195], v[116:119]
	v_mfma_f32_16x16x32_bf16 v[108:111], v[176:179], v[200:203], v[108:111]
	v_mfma_f32_16x16x32_bf16 v[100:103], v[184:187], v[200:203], v[100:103]
	v_mfma_f32_16x16x32_bf16 v[92:95], v[176:179], v[218:221], v[92:95]
	v_mfma_f32_16x16x32_bf16 v[84:87], v[184:187], v[218:221], v[84:87]
	v_mfma_f32_16x16x32_bf16 v[76:79], v[176:179], v[226:229], v[76:79]
	v_mfma_f32_16x16x32_bf16 v[68:71], v[184:187], v[226:229], v[68:71]
	s_setprio 0
	s_barrier
	s_add_u32 s18, s16, 0x8000
	s_addc_u32 s19, s17, 0
	s_add_i32 s48, s48, s27
	v_lshl_add_u64 v[208:209], s[18:19], 0, v[136:137]
	s_mov_b32 m0, s48
	ds_read_b128 v[188:191], v159 offset:49152
	ds_read_b128 v[192:195], v159 offset:50176
	ds_read_b128 v[196:199], v159 offset:51200
	ds_read_b128 v[200:203], v159 offset:52224
	ds_read_b128 v[214:217], v159 offset:53248
	ds_read_b128 v[218:221], v159 offset:54272
	ds_read_b128 v[222:225], v159 offset:55296
	ds_read_b128 v[226:229], v159 offset:56320
	global_load_lds_dwordx4 v[208:209], off
	s_add_i32 m0, s48, 0x2000
	s_add_u32 s16, s16, 0xc000
	v_lshl_add_u64 v[208:209], s[18:19], 0, v[132:133]
	s_addc_u32 s17, s17, 0
	s_add_i32 s18, s49, s27
	global_load_lds_dwordx4 v[208:209], off
	v_lshl_add_u64 v[208:209], s[16:17], 0, v[136:137]
	s_mov_b32 m0, s18
	v_lshl_add_u64 v[204:205], v[204:205], 0, s[74:75]
	global_load_lds_dwordx4 v[208:209], off
	v_lshl_add_u64 v[208:209], s[16:17], 0, v[132:133]
	s_add_i32 m0, s18, 0x2000
	s_nop 0
	global_load_lds_dwordx4 v[208:209], off
	s_mov_b32 m0, s38
	s_nop 0
	global_load_lds_dwordx4 v[204:205], off
	v_lshl_add_u64 v[204:205], v[206:207], 0, s[74:75]
	s_mov_b32 m0, s39
	s_nop 0
	global_load_lds_dwordx4 v[204:205], off
	s_waitcnt vmcnt(8)
	s_waitcnt lgkmcnt(0)
	s_barrier
	s_setprio 1
	s_waitcnt lgkmcnt(0)
	v_mfma_f32_16x16x32_bf16 v[64:67], v[154:157], v[188:191], v[64:67]
	v_mfma_f32_16x16x32_bf16 v[56:59], v[164:167], v[188:191], v[56:59]
	v_mfma_f32_16x16x32_bf16 v[48:51], v[154:157], v[196:199], v[48:51]
	v_mfma_f32_16x16x32_bf16 v[40:43], v[164:167], v[196:199], v[40:43]
	v_mfma_f32_16x16x32_bf16 v[32:35], v[154:157], v[214:217], v[32:35]
	v_mfma_f32_16x16x32_bf16 v[24:27], v[164:167], v[214:217], v[24:27]
	v_mfma_f32_16x16x32_bf16 v[16:19], v[154:157], v[222:225], v[16:19]
	v_mfma_f32_16x16x32_bf16 v[8:11], v[164:167], v[222:225], v[8:11]
	v_mfma_f32_16x16x32_bf16 v[64:67], v[160:163], v[192:195], v[64:67]
	v_mfma_f32_16x16x32_bf16 v[56:59], v[168:171], v[192:195], v[56:59]
	v_mfma_f32_16x16x32_bf16 v[48:51], v[160:163], v[200:203], v[48:51]
	v_mfma_f32_16x16x32_bf16 v[40:43], v[168:171], v[200:203], v[40:43]
	v_mfma_f32_16x16x32_bf16 v[32:35], v[160:163], v[218:221], v[32:35]
	v_mfma_f32_16x16x32_bf16 v[24:27], v[168:171], v[218:221], v[24:27]
	v_mfma_f32_16x16x32_bf16 v[16:19], v[160:163], v[226:229], v[16:19]
	v_mfma_f32_16x16x32_bf16 v[8:11], v[168:171], v[226:229], v[8:11]
	s_setprio 0
	s_setprio 1
	v_mfma_f32_16x16x32_bf16 v[60:63], v[172:175], v[188:191], v[60:63]
	v_mfma_f32_16x16x32_bf16 v[52:55], v[180:183], v[188:191], v[52:55]
	v_mfma_f32_16x16x32_bf16 v[44:47], v[172:175], v[196:199], v[44:47]
	v_mfma_f32_16x16x32_bf16 v[36:39], v[180:183], v[196:199], v[36:39]
	v_mfma_f32_16x16x32_bf16 v[28:31], v[172:175], v[214:217], v[28:31]
	v_mfma_f32_16x16x32_bf16 v[20:23], v[180:183], v[214:217], v[20:23]
	v_mfma_f32_16x16x32_bf16 v[12:15], v[172:175], v[222:225], v[12:15]
	v_mfma_f32_16x16x32_bf16 v[4:7], v[180:183], v[222:225], v[4:7]
	v_mfma_f32_16x16x32_bf16 v[60:63], v[176:179], v[192:195], v[60:63]
	v_mfma_f32_16x16x32_bf16 v[52:55], v[184:187], v[192:195], v[52:55]
	v_mfma_f32_16x16x32_bf16 v[44:47], v[176:179], v[200:203], v[44:47]
	v_mfma_f32_16x16x32_bf16 v[36:39], v[184:187], v[200:203], v[36:39]
	v_mfma_f32_16x16x32_bf16 v[28:31], v[176:179], v[218:221], v[28:31]
	v_mfma_f32_16x16x32_bf16 v[20:23], v[184:187], v[218:221], v[20:23]
	v_mfma_f32_16x16x32_bf16 v[12:15], v[176:179], v[226:229], v[12:15]
	v_mfma_f32_16x16x32_bf16 v[4:7], v[184:187], v[226:229], v[4:7]
	s_setprio 0
	s_barrier
	s_add_i32 s47, s47, 2
	s_add_u32 s45, s45, 0x10000
	s_addc_u32 s46, s46, 0
	s_add_u32 s14, s14, 0x100
	s_addc_u32 s15, s15, 0
	s_cmp_gt_u32 s47, 29
	.p2align	6

.LBB0_225:
	s_add_u32 s18, s22, 0xc000
	s_addc_u32 s19, s23, 0
	s_add_u32 s2, s20, 0x10000
	s_addc_u32 s3, s21, 0
	s_mov_b32 s24, -2
	s_add_u32 s14, s18, 0x4000
	s_addc_u32 s15, s19, 0
	s_cmpk_eq_i32 s24, 0x54
	s_cselect_b32 s22, s30, s14
	s_cselect_b32 s23, s31, s15
	s_cselect_b32 s20, s38, s2
	s_cselect_b32 s21, s39, s3
	s_add_u32 s14, s22, 0x8000
	s_addc_u32 s15, s23, 0
	s_add_i32 s25, 0, 0x10000
	s_add_i32 s50, 0, 0x14000
	v_add_u32_e32 v144, s25, v174
	v_add_u32_e32 v160, s50, v174
	ds_read_b128 v[132:135], v144
	ds_read_b128 v[136:139], v144 offset:1024
	ds_read_b128 v[140:143], v144 offset:2048
	ds_read_b128 v[144:147], v144 offset:3072
	ds_read_b128 v[148:151], v160
	ds_read_b128 v[152:155], v160 offset:1024
	ds_read_b128 v[156:159], v160 offset:2048
	ds_read_b128 v[160:163], v160 offset:3072
	v_lshl_add_u64 v[206:207], s[18:19], 0, v[166:167]
	s_add_i32 m0, s65, 0xc000
	ds_read_b128 v[170:173], v182
	ds_read_b128 v[186:189], v182 offset:1024
	ds_read_b128 v[190:193], v182 offset:2048
	ds_read_b128 v[194:197], v182 offset:3072
	ds_read_b128 v[198:201], v182 offset:4096
	ds_read_b128 v[202:205], v182 offset:5120
	ds_read_b128 v[214:217], v182 offset:6144
	ds_read_b128 v[218:221], v182 offset:7168
	global_load_lds_dwordx4 v[206:207], off
	v_lshl_add_u64 v[206:207], s[18:19], 0, v[168:169]
	s_add_i32 m0, s65, 0xe000
	s_nop 0
	global_load_lds_dwordx4 v[206:207], off
	s_waitcnt vmcnt(8)
	s_waitcnt lgkmcnt(0)
	s_barrier
	s_setprio 1
	s_waitcnt lgkmcnt(0)
	v_mfma_f32_16x16x32_bf16 v[128:131], v[132:135], v[170:173], 0
	v_mfma_f32_16x16x32_bf16 v[124:127], v[140:143], v[170:173], 0
	v_mfma_f32_16x16x32_bf16 v[108:111], v[132:135], v[190:193], 0
	v_mfma_f32_16x16x32_bf16 v[116:119], v[140:143], v[190:193], 0
	v_mfma_f32_16x16x32_bf16 v[92:95], v[132:135], v[198:201], 0
	v_mfma_f32_16x16x32_bf16 v[88:91], v[140:143], v[198:201], 0
	v_mfma_f32_16x16x32_bf16 v[76:79], v[132:135], v[214:217], 0
	v_mfma_f32_16x16x32_bf16 v[80:83], v[140:143], v[214:217], 0
	v_mfma_f32_16x16x32_bf16 v[128:131], v[136:139], v[186:189], v[128:131]
	v_mfma_f32_16x16x32_bf16 v[124:127], v[144:147], v[186:189], v[124:127]
	v_mfma_f32_16x16x32_bf16 v[108:111], v[136:139], v[194:197], v[108:111]
	v_mfma_f32_16x16x32_bf16 v[116:119], v[144:147], v[194:197], v[116:119]
	v_mfma_f32_16x16x32_bf16 v[92:95], v[136:139], v[202:205], v[92:95]
	v_mfma_f32_16x16x32_bf16 v[88:91], v[144:147], v[202:205], v[88:91]
	v_mfma_f32_16x16x32_bf16 v[76:79], v[136:139], v[218:221], v[76:79]
	v_mfma_f32_16x16x32_bf16 v[80:83], v[144:147], v[218:221], v[80:83]
	s_setprio 0
	s_setprio 1
	v_mfma_f32_16x16x32_bf16 v[120:123], v[148:151], v[170:173], 0
	v_mfma_f32_16x16x32_bf16 v[104:107], v[156:159], v[170:173], 0
	v_mfma_f32_16x16x32_bf16 v[100:103], v[148:151], v[190:193], 0
	v_mfma_f32_16x16x32_bf16 v[96:99], v[156:159], v[190:193], 0
	v_mfma_f32_16x16x32_bf16 v[84:87], v[148:151], v[198:201], 0
	v_mfma_f32_16x16x32_bf16 v[72:75], v[156:159], v[198:201], 0
	v_mfma_f32_16x16x32_bf16 v[68:71], v[148:151], v[214:217], 0
	v_mfma_f32_16x16x32_bf16 v[64:67], v[156:159], v[214:217], 0
	v_mfma_f32_16x16x32_bf16 v[120:123], v[152:155], v[186:189], v[120:123]
	v_mfma_f32_16x16x32_bf16 v[104:107], v[160:163], v[186:189], v[104:107]
	v_mfma_f32_16x16x32_bf16 v[100:103], v[152:155], v[194:197], v[100:103]
	v_mfma_f32_16x16x32_bf16 v[96:99], v[160:163], v[194:197], v[96:99]
	v_mfma_f32_16x16x32_bf16 v[84:87], v[152:155], v[202:205], v[84:87]
	v_mfma_f32_16x16x32_bf16 v[72:75], v[160:163], v[202:205], v[72:75]
	v_mfma_f32_16x16x32_bf16 v[68:71], v[152:155], v[218:221], v[68:71]
	v_mfma_f32_16x16x32_bf16 v[64:67], v[160:163], v[218:221], v[64:67]
	s_setprio 0
	s_barrier
	s_add_i32 s25, s25, s64
	v_lshl_add_u64 v[206:207], s[20:21], 0, v[2:3]
	s_mov_b32 m0, s25
	ds_read_b128 v[170:173], v182 offset:16384
	ds_read_b128 v[186:189], v182 offset:17408
	ds_read_b128 v[190:193], v182 offset:18432
	ds_read_b128 v[194:197], v182 offset:19456
	ds_read_b128 v[198:201], v182 offset:20480
	ds_read_b128 v[202:205], v182 offset:21504
	ds_read_b128 v[214:217], v182 offset:22528
	ds_read_b128 v[218:221], v182 offset:23552
	global_load_lds_dwordx4 v[206:207], off
	s_add_i32 m0, s25, 0x2000
	s_add_u32 s26, s20, 0x4000
	v_lshl_add_u64 v[206:207], s[20:21], 0, v[164:165]
	s_addc_u32 s27, s21, 0
	s_add_i32 s25, s50, s64
	global_load_lds_dwordx4 v[206:207], off
	v_lshl_add_u64 v[206:207], s[26:27], 0, v[2:3]
	s_mov_b32 m0, s25
	s_nop 0
	global_load_lds_dwordx4 v[206:207], off
	v_lshl_add_u64 v[206:207], s[26:27], 0, v[164:165]
	s_add_i32 m0, s25, 0x2000
	s_nop 0
	global_load_lds_dwordx4 v[206:207], off
	v_lshl_add_u64 v[206:207], s[22:23], 0, v[2:3]
	s_mov_b32 m0, s65
	s_nop 0
	global_load_lds_dwordx4 v[206:207], off
	v_lshl_add_u64 v[206:207], s[22:23], 0, v[164:165]
	s_mov_b32 m0, s34
	s_nop 0
	global_load_lds_dwordx4 v[206:207], off
	s_waitcnt vmcnt(8)
	s_waitcnt lgkmcnt(0)
	s_barrier
	s_setprio 1
	s_waitcnt lgkmcnt(0)
	v_mfma_f32_16x16x32_bf16 v[60:63], v[132:135], v[170:173], 0
	v_mfma_f32_16x16x32_bf16 v[56:59], v[140:143], v[170:173], 0
	v_mfma_f32_16x16x32_bf16 v[44:47], v[132:135], v[190:193], 0
	v_mfma_f32_16x16x32_bf16 v[48:51], v[140:143], v[190:193], 0
	v_mfma_f32_16x16x32_bf16 v[28:31], v[132:135], v[198:201], 0
	v_mfma_f32_16x16x32_bf16 v[24:27], v[140:143], v[198:201], 0
	v_mfma_f32_16x16x32_bf16 v[112:115], v[132:135], v[214:217], 0
	v_mfma_f32_16x16x32_bf16 v[16:19], v[140:143], v[214:217], 0
	v_mfma_f32_16x16x32_bf16 v[60:63], v[136:139], v[186:189], v[60:63]
	v_mfma_f32_16x16x32_bf16 v[56:59], v[144:147], v[186:189], v[56:59]
	v_mfma_f32_16x16x32_bf16 v[44:47], v[136:139], v[194:197], v[44:47]
	v_mfma_f32_16x16x32_bf16 v[48:51], v[144:147], v[194:197], v[48:51]
	v_mfma_f32_16x16x32_bf16 v[28:31], v[136:139], v[202:205], v[28:31]
	v_mfma_f32_16x16x32_bf16 v[24:27], v[144:147], v[202:205], v[24:27]
	v_mfma_f32_16x16x32_bf16 v[112:115], v[136:139], v[218:221], v[112:115]
	v_mfma_f32_16x16x32_bf16 v[16:19], v[144:147], v[218:221], v[16:19]
	s_setprio 0
	s_setprio 1
	v_mfma_f32_16x16x32_bf16 v[52:55], v[148:151], v[170:173], 0
	v_mfma_f32_16x16x32_bf16 v[40:43], v[156:159], v[170:173], 0
	v_mfma_f32_16x16x32_bf16 v[36:39], v[148:151], v[190:193], 0
	v_mfma_f32_16x16x32_bf16 v[32:35], v[156:159], v[190:193], 0
	v_mfma_f32_16x16x32_bf16 v[20:23], v[148:151], v[198:201], 0
	v_mfma_f32_16x16x32_bf16 v[12:15], v[156:159], v[198:201], 0
	v_mfma_f32_16x16x32_bf16 v[4:7], v[148:151], v[214:217], 0
	v_mfma_f32_16x16x32_bf16 v[8:11], v[156:159], v[214:217], 0
	v_mfma_f32_16x16x32_bf16 v[52:55], v[152:155], v[186:189], v[52:55]
	v_mfma_f32_16x16x32_bf16 v[40:43], v[160:163], v[186:189], v[40:43]
	v_mfma_f32_16x16x32_bf16 v[36:39], v[152:155], v[194:197], v[36:39]
	v_mfma_f32_16x16x32_bf16 v[32:35], v[160:163], v[194:197], v[32:35]
	v_mfma_f32_16x16x32_bf16 v[20:23], v[152:155], v[202:205], v[20:23]
	v_mfma_f32_16x16x32_bf16 v[12:15], v[160:163], v[202:205], v[12:15]
	v_mfma_f32_16x16x32_bf16 v[4:7], v[152:155], v[218:221], v[4:7]
	v_mfma_f32_16x16x32_bf16 v[8:11], v[160:163], v[218:221], v[8:11]
	s_setprio 0
	s_barrier
	s_add_i32 s25, 0, 0x18000
	s_add_i32 s26, 0, 0x1c000
	v_add_u32_e32 v144, s25, v174
	v_add_u32_e32 v160, s26, v174
	ds_read_b128 v[132:135], v144
	ds_read_b128 v[136:139], v144 offset:1024
	ds_read_b128 v[140:143], v144 offset:2048
	ds_read_b128 v[144:147], v144 offset:3072
	ds_read_b128 v[148:151], v160
	ds_read_b128 v[152:155], v160 offset:1024
	ds_read_b128 v[156:159], v160 offset:2048
	ds_read_b128 v[160:163], v160 offset:3072
	s_add_u32 s22, s22, 0x4000
	s_addc_u32 s23, s23, 0
	s_mov_b32 m0, s35
	v_lshl_add_u64 v[206:207], s[22:23], 0, v[2:3]
	ds_read_b128 v[170:173], v182 offset:32768
	ds_read_b128 v[186:189], v182 offset:33792
	ds_read_b128 v[190:193], v182 offset:34816
	ds_read_b128 v[194:197], v182 offset:35840
	ds_read_b128 v[198:201], v182 offset:36864
	ds_read_b128 v[202:205], v182 offset:37888
	ds_read_b128 v[214:217], v182 offset:38912
	ds_read_b128 v[218:221], v182 offset:39936
	global_load_lds_dwordx4 v[206:207], off
	v_lshl_add_u64 v[206:207], s[22:23], 0, v[164:165]
	s_mov_b32 m0, s40
	s_nop 0
	global_load_lds_dwordx4 v[206:207], off
	s_waitcnt vmcnt(8)
	s_waitcnt lgkmcnt(0)
	s_barrier
	s_setprio 1
	s_waitcnt lgkmcnt(0)
	v_mfma_f32_16x16x32_bf16 v[128:131], v[132:135], v[170:173], v[128:131]
	v_mfma_f32_16x16x32_bf16 v[124:127], v[140:143], v[170:173], v[124:127]
	v_mfma_f32_16x16x32_bf16 v[108:111], v[132:135], v[190:193], v[108:111]
	v_mfma_f32_16x16x32_bf16 v[116:119], v[140:143], v[190:193], v[116:119]
	v_mfma_f32_16x16x32_bf16 v[92:95], v[132:135], v[198:201], v[92:95]
	v_mfma_f32_16x16x32_bf16 v[88:91], v[140:143], v[198:201], v[88:91]
	v_mfma_f32_16x16x32_bf16 v[76:79], v[132:135], v[214:217], v[76:79]
	v_mfma_f32_16x16x32_bf16 v[80:83], v[140:143], v[214:217], v[80:83]
	v_mfma_f32_16x16x32_bf16 v[128:131], v[136:139], v[186:189], v[128:131]
	v_mfma_f32_16x16x32_bf16 v[124:127], v[144:147], v[186:189], v[124:127]
	v_mfma_f32_16x16x32_bf16 v[108:111], v[136:139], v[194:197], v[108:111]
	v_mfma_f32_16x16x32_bf16 v[116:119], v[144:147], v[194:197], v[116:119]
	v_mfma_f32_16x16x32_bf16 v[92:95], v[136:139], v[202:205], v[92:95]
	v_mfma_f32_16x16x32_bf16 v[88:91], v[144:147], v[202:205], v[88:91]
	v_mfma_f32_16x16x32_bf16 v[76:79], v[136:139], v[218:221], v[76:79]
	v_mfma_f32_16x16x32_bf16 v[80:83], v[144:147], v[218:221], v[80:83]
	s_setprio 0
	s_setprio 1
	v_mfma_f32_16x16x32_bf16 v[120:123], v[148:151], v[170:173], v[120:123]
	v_mfma_f32_16x16x32_bf16 v[104:107], v[156:159], v[170:173], v[104:107]
	v_mfma_f32_16x16x32_bf16 v[100:103], v[148:151], v[190:193], v[100:103]
	v_mfma_f32_16x16x32_bf16 v[96:99], v[156:159], v[190:193], v[96:99]
	v_mfma_f32_16x16x32_bf16 v[84:87], v[148:151], v[198:201], v[84:87]
	v_mfma_f32_16x16x32_bf16 v[72:75], v[156:159], v[198:201], v[72:75]
	v_mfma_f32_16x16x32_bf16 v[68:71], v[148:151], v[214:217], v[68:71]
	v_mfma_f32_16x16x32_bf16 v[64:67], v[156:159], v[214:217], v[64:67]
	v_mfma_f32_16x16x32_bf16 v[120:123], v[152:155], v[186:189], v[120:123]
	v_mfma_f32_16x16x32_bf16 v[104:107], v[160:163], v[186:189], v[104:107]
	v_mfma_f32_16x16x32_bf16 v[100:103], v[152:155], v[194:197], v[100:103]
	v_mfma_f32_16x16x32_bf16 v[96:99], v[160:163], v[194:197], v[96:99]
	v_mfma_f32_16x16x32_bf16 v[84:87], v[152:155], v[202:205], v[84:87]
	v_mfma_f32_16x16x32_bf16 v[72:75], v[160:163], v[202:205], v[72:75]
	v_mfma_f32_16x16x32_bf16 v[68:71], v[152:155], v[218:221], v[68:71]
	v_mfma_f32_16x16x32_bf16 v[64:67], v[160:163], v[218:221], v[64:67]
	s_setprio 0
	s_barrier
	s_add_u32 s22, s20, 0x8000
	s_addc_u32 s23, s21, 0
	s_add_i32 s25, s25, s64
	v_lshl_add_u64 v[206:207], s[22:23], 0, v[2:3]
	s_mov_b32 m0, s25
	ds_read_b128 v[170:173], v182 offset:49152
	ds_read_b128 v[186:189], v182 offset:50176
	ds_read_b128 v[190:193], v182 offset:51200
	ds_read_b128 v[194:197], v182 offset:52224
	ds_read_b128 v[198:201], v182 offset:53248
	ds_read_b128 v[202:205], v182 offset:54272
	ds_read_b128 v[214:217], v182 offset:55296
	ds_read_b128 v[218:221], v182 offset:56320
	global_load_lds_dwordx4 v[206:207], off
	s_add_i32 m0, s25, 0x2000
	s_add_u32 s20, s20, 0xc000
	v_lshl_add_u64 v[206:207], s[22:23], 0, v[164:165]
	s_addc_u32 s21, s21, 0
	s_add_i32 s22, s26, s64
	global_load_lds_dwordx4 v[206:207], off
	v_lshl_add_u64 v[206:207], s[20:21], 0, v[2:3]
	s_mov_b32 m0, s22
	s_nop 0
	global_load_lds_dwordx4 v[206:207], off
	v_lshl_add_u64 v[206:207], s[20:21], 0, v[164:165]
	s_add_i32 m0, s22, 0x2000
	s_nop 0
	global_load_lds_dwordx4 v[206:207], off
	v_lshl_add_u64 v[206:207], s[14:15], 0, v[2:3]
	s_mov_b32 m0, s41
	s_nop 0
	global_load_lds_dwordx4 v[206:207], off
	v_lshl_add_u64 v[206:207], s[14:15], 0, v[164:165]
	s_mov_b32 m0, s46
	s_nop 0
	global_load_lds_dwordx4 v[206:207], off
	s_waitcnt vmcnt(8)
	s_waitcnt lgkmcnt(0)
	s_barrier
	s_setprio 1
	s_waitcnt lgkmcnt(0)
	v_mfma_f32_16x16x32_bf16 v[60:63], v[132:135], v[170:173], v[60:63]
	v_mfma_f32_16x16x32_bf16 v[56:59], v[140:143], v[170:173], v[56:59]
	v_mfma_f32_16x16x32_bf16 v[44:47], v[132:135], v[190:193], v[44:47]
	v_mfma_f32_16x16x32_bf16 v[48:51], v[140:143], v[190:193], v[48:51]
	v_mfma_f32_16x16x32_bf16 v[28:31], v[132:135], v[198:201], v[28:31]
	v_mfma_f32_16x16x32_bf16 v[24:27], v[140:143], v[198:201], v[24:27]
	v_mfma_f32_16x16x32_bf16 v[112:115], v[132:135], v[214:217], v[112:115]
	v_mfma_f32_16x16x32_bf16 v[16:19], v[140:143], v[214:217], v[16:19]
	v_mfma_f32_16x16x32_bf16 v[60:63], v[136:139], v[186:189], v[60:63]
	v_mfma_f32_16x16x32_bf16 v[56:59], v[144:147], v[186:189], v[56:59]
	v_mfma_f32_16x16x32_bf16 v[44:47], v[136:139], v[194:197], v[44:47]
	v_mfma_f32_16x16x32_bf16 v[48:51], v[144:147], v[194:197], v[48:51]
	v_mfma_f32_16x16x32_bf16 v[28:31], v[136:139], v[202:205], v[28:31]
	v_mfma_f32_16x16x32_bf16 v[24:27], v[144:147], v[202:205], v[24:27]
	v_mfma_f32_16x16x32_bf16 v[112:115], v[136:139], v[218:221], v[112:115]
	v_mfma_f32_16x16x32_bf16 v[16:19], v[144:147], v[218:221], v[16:19]
	s_setprio 0
	s_setprio 1
	v_mfma_f32_16x16x32_bf16 v[52:55], v[148:151], v[170:173], v[52:55]
	v_mfma_f32_16x16x32_bf16 v[40:43], v[156:159], v[170:173], v[40:43]
	v_mfma_f32_16x16x32_bf16 v[36:39], v[148:151], v[190:193], v[36:39]
	v_mfma_f32_16x16x32_bf16 v[32:35], v[156:159], v[190:193], v[32:35]
	v_mfma_f32_16x16x32_bf16 v[20:23], v[148:151], v[198:201], v[20:23]
	v_mfma_f32_16x16x32_bf16 v[12:15], v[156:159], v[198:201], v[12:15]
	v_mfma_f32_16x16x32_bf16 v[4:7], v[148:151], v[214:217], v[4:7]
	v_mfma_f32_16x16x32_bf16 v[8:11], v[156:159], v[214:217], v[8:11]
	v_mfma_f32_16x16x32_bf16 v[52:55], v[152:155], v[186:189], v[52:55]
	v_mfma_f32_16x16x32_bf16 v[40:43], v[160:163], v[186:189], v[40:43]
	v_mfma_f32_16x16x32_bf16 v[36:39], v[152:155], v[194:197], v[36:39]
	v_mfma_f32_16x16x32_bf16 v[32:35], v[160:163], v[194:197], v[32:35]
	v_mfma_f32_16x16x32_bf16 v[20:23], v[152:155], v[202:205], v[20:23]
	v_mfma_f32_16x16x32_bf16 v[12:15], v[160:163], v[202:205], v[12:15]
	v_mfma_f32_16x16x32_bf16 v[4:7], v[152:155], v[218:221], v[4:7]
	v_mfma_f32_16x16x32_bf16 v[8:11], v[160:163], v[218:221], v[8:11]
	s_setprio 0
	s_barrier
	s_add_i32 s24, s24, 2
	s_add_u32 s18, s18, 0x10000
	s_addc_u32 s19, s19, 0
	s_add_u32 s2, s2, 0x10000
	s_addc_u32 s3, s3, 0
	s_cmpk_gt_u32 s24, 0x55
	.p2align	6

.LBB0_337:
	s_ashr_i32 s5, s4, 31
	s_lshl_b64 s[16:17], s[4:5], 20
	s_add_u32 s16, s31, s16
	s_addc_u32 s17, s34, s17
	s_and_b64 s[20:21], s[10:11], exec
	s_cselect_b32 s5, s17, s23
	s_cselect_b32 s15, s16, s22
	s_ashr_i32 s7, s6, 31
	s_lshl_b64 s[20:21], s[6:7], 20
	s_add_u32 s20, s35, s20
	s_addc_u32 s21, s36, s21
	s_and_b64 s[24:25], s[10:11], exec
	s_cselect_b32 s7, s21, s13
	s_cselect_b32 s26, s20, s12
	s_add_u32 s27, s12, 0x10000
	s_addc_u32 s50, s13, 0
	s_add_u32 s12, s22, 0x80080
	s_addc_u32 s13, s23, 0
	s_mov_b32 s51, -2
	s_add_u32 s22, s12, 0xfff80080
	s_addc_u32 s23, s13, -1
	s_add_i32 s52, 0, 0x10000
	s_cmp_eq_u32 s51, 28
	s_cselect_b32 s25, s5, s23
	s_cselect_b32 s24, s15, s22
	v_add_u32_e32 v2, s52, v205
	s_cselect_b32 s23, s7, s50
	s_cselect_b32 s22, s26, s27
	s_add_i32 s54, 0, 0x14000
	ds_read_b128 v[92:95], v2
	ds_read_b128 v[96:99], v2 offset:1024
	ds_read_b128 v[120:123], v2 offset:2048
	ds_read_b128 v[132:135], v2 offset:3072
	v_add_u32_e32 v2, s54, v205
	ds_read_b128 v[140:143], v2
	ds_read_b128 v[152:155], v2 offset:1024
	ds_read_b128 v[156:159], v2 offset:2048
	ds_read_b128 v[160:163], v2 offset:3072
	v_lshl_add_u64 v[206:207], s[12:13], 0, v[220:221]
	s_add_i32 m0, s19, 0xc000
	ds_read_b128 v[164:167], v215
	ds_read_b128 v[168:171], v215 offset:1024
	ds_read_b128 v[172:175], v215 offset:2048
	ds_read_b128 v[176:179], v215 offset:3072
	ds_read_b128 v[180:183], v215 offset:4096
	ds_read_b128 v[184:187], v215 offset:5120
	ds_read_b128 v[188:191], v215 offset:6144
	ds_read_b128 v[192:195], v215 offset:7168
	global_load_lds_dwordx4 v[206:207], off
	v_lshl_add_u64 v[206:207], s[12:13], 0, v[222:223]
	s_add_i32 m0, s19, 0xe000
	s_nop 0
	global_load_lds_dwordx4 v[206:207], off
	s_waitcnt vmcnt(8)
	s_waitcnt lgkmcnt(0)
	s_barrier
	s_setprio 1
	s_waitcnt lgkmcnt(0)
	v_mfma_f32_16x16x32_bf16 v[148:151], v[92:95], v[164:167], 0
	v_mfma_f32_16x16x32_bf16 v[144:147], v[120:123], v[164:167], 0
	v_mfma_f32_16x16x32_bf16 v[124:127], v[92:95], v[172:175], 0
	v_mfma_f32_16x16x32_bf16 v[116:119], v[120:123], v[172:175], 0
	v_mfma_f32_16x16x32_bf16 v[104:107], v[92:95], v[180:183], 0
	v_mfma_f32_16x16x32_bf16 v[100:103], v[120:123], v[180:183], 0
	v_mfma_f32_16x16x32_bf16 v[80:83], v[92:95], v[188:191], 0
	v_mfma_f32_16x16x32_bf16 v[76:79], v[120:123], v[188:191], 0
	v_mfma_f32_16x16x32_bf16 v[148:151], v[96:99], v[168:171], v[148:151]
	v_mfma_f32_16x16x32_bf16 v[144:147], v[132:135], v[168:171], v[144:147]
	v_mfma_f32_16x16x32_bf16 v[124:127], v[96:99], v[176:179], v[124:127]
	v_mfma_f32_16x16x32_bf16 v[116:119], v[132:135], v[176:179], v[116:119]
	v_mfma_f32_16x16x32_bf16 v[104:107], v[96:99], v[184:187], v[104:107]
	v_mfma_f32_16x16x32_bf16 v[100:103], v[132:135], v[184:187], v[100:103]
	v_mfma_f32_16x16x32_bf16 v[80:83], v[96:99], v[192:195], v[80:83]
	v_mfma_f32_16x16x32_bf16 v[76:79], v[132:135], v[192:195], v[76:79]
	s_setprio 0
	s_setprio 1
	v_mfma_f32_16x16x32_bf16 v[136:139], v[140:143], v[164:167], 0
	v_mfma_f32_16x16x32_bf16 v[128:131], v[156:159], v[164:167], 0
	v_mfma_f32_16x16x32_bf16 v[112:115], v[140:143], v[172:175], 0
	v_mfma_f32_16x16x32_bf16 v[108:111], v[156:159], v[172:175], 0
	v_mfma_f32_16x16x32_bf16 v[88:91], v[140:143], v[180:183], 0
	v_mfma_f32_16x16x32_bf16 v[84:87], v[156:159], v[180:183], 0
	v_mfma_f32_16x16x32_bf16 v[72:75], v[140:143], v[188:191], 0
	v_mfma_f32_16x16x32_bf16 v[68:71], v[156:159], v[188:191], 0
	v_mfma_f32_16x16x32_bf16 v[136:139], v[152:155], v[168:171], v[136:139]
	v_mfma_f32_16x16x32_bf16 v[128:131], v[160:163], v[168:171], v[128:131]
	v_mfma_f32_16x16x32_bf16 v[112:115], v[152:155], v[176:179], v[112:115]
	v_mfma_f32_16x16x32_bf16 v[108:111], v[160:163], v[176:179], v[108:111]
	v_mfma_f32_16x16x32_bf16 v[88:91], v[152:155], v[184:187], v[88:91]
	v_mfma_f32_16x16x32_bf16 v[84:87], v[160:163], v[184:187], v[84:87]
	v_mfma_f32_16x16x32_bf16 v[72:75], v[152:155], v[192:195], v[72:75]
	v_mfma_f32_16x16x32_bf16 v[68:71], v[160:163], v[192:195], v[68:71]
	s_setprio 0
	s_barrier
	s_add_i32 s52, s52, s37
	v_lshl_add_u64 v[206:207], s[22:23], 0, v[198:199]
	s_mov_b32 m0, s52
	ds_read_b128 v[164:167], v215 offset:16384
	ds_read_b128 v[168:171], v215 offset:17408
	ds_read_b128 v[172:175], v215 offset:18432
	ds_read_b128 v[176:179], v215 offset:19456
	ds_read_b128 v[180:183], v215 offset:20480
	ds_read_b128 v[184:187], v215 offset:21504
	ds_read_b128 v[188:191], v215 offset:22528
	ds_read_b128 v[192:195], v215 offset:23552
	global_load_lds_dwordx4 v[206:207], off
	s_add_i32 m0, s52, 0x2000
	s_add_u32 s52, s22, 0x4000
	v_lshl_add_u64 v[206:207], s[22:23], 0, v[202:203]
	s_addc_u32 s53, s23, 0
	s_add_i32 s54, s54, s37
	global_load_lds_dwordx4 v[206:207], off
	v_lshl_add_u64 v[206:207], s[52:53], 0, v[198:199]
	s_mov_b32 m0, s54
	v_lshl_add_u64 v[208:209], s[24:25], 0, v[200:201]
	global_load_lds_dwordx4 v[206:207], off
	v_lshl_add_u64 v[206:207], s[52:53], 0, v[202:203]
	s_add_i32 m0, s54, 0x2000
	s_nop 0
	global_load_lds_dwordx4 v[206:207], off
	v_lshl_add_u64 v[206:207], s[24:25], 0, v[196:197]
	s_mov_b32 m0, s19
	s_nop 0
	global_load_lds_dwordx4 v[206:207], off
	s_mov_b32 m0, s38
	s_nop 0
	global_load_lds_dwordx4 v[208:209], off
	s_waitcnt vmcnt(8)
	s_waitcnt lgkmcnt(0)
	s_barrier
	s_setprio 1
	s_waitcnt lgkmcnt(0)
	v_mfma_f32_16x16x32_bf16 v[64:67], v[92:95], v[164:167], 0
	v_mfma_f32_16x16x32_bf16 v[60:63], v[120:123], v[164:167], 0
	v_mfma_f32_16x16x32_bf16 v[48:51], v[92:95], v[172:175], 0
	v_mfma_f32_16x16x32_bf16 v[44:47], v[120:123], v[172:175], 0
	v_mfma_f32_16x16x32_bf16 v[32:35], v[92:95], v[180:183], 0
	v_mfma_f32_16x16x32_bf16 v[28:31], v[120:123], v[180:183], 0
	v_mfma_f32_16x16x32_bf16 v[16:19], v[92:95], v[188:191], 0
	v_mfma_f32_16x16x32_bf16 v[12:15], v[120:123], v[188:191], 0
	v_mfma_f32_16x16x32_bf16 v[64:67], v[96:99], v[168:171], v[64:67]
	v_mfma_f32_16x16x32_bf16 v[60:63], v[132:135], v[168:171], v[60:63]
	v_mfma_f32_16x16x32_bf16 v[48:51], v[96:99], v[176:179], v[48:51]
	v_mfma_f32_16x16x32_bf16 v[44:47], v[132:135], v[176:179], v[44:47]
	v_mfma_f32_16x16x32_bf16 v[32:35], v[96:99], v[184:187], v[32:35]
	v_mfma_f32_16x16x32_bf16 v[28:31], v[132:135], v[184:187], v[28:31]
	v_mfma_f32_16x16x32_bf16 v[16:19], v[96:99], v[192:195], v[16:19]
	v_mfma_f32_16x16x32_bf16 v[12:15], v[132:135], v[192:195], v[12:15]
	s_setprio 0
	s_setprio 1
	v_mfma_f32_16x16x32_bf16 v[56:59], v[140:143], v[164:167], 0
	v_mfma_f32_16x16x32_bf16 v[52:55], v[156:159], v[164:167], 0
	v_mfma_f32_16x16x32_bf16 v[40:43], v[140:143], v[172:175], 0
	v_mfma_f32_16x16x32_bf16 v[36:39], v[156:159], v[172:175], 0
	v_mfma_f32_16x16x32_bf16 v[24:27], v[140:143], v[180:183], 0
	v_mfma_f32_16x16x32_bf16 v[20:23], v[156:159], v[180:183], 0
	v_mfma_f32_16x16x32_bf16 v[8:11], v[140:143], v[188:191], 0
	v_mfma_f32_16x16x32_bf16 v[4:7], v[156:159], v[188:191], 0
	v_mfma_f32_16x16x32_bf16 v[56:59], v[152:155], v[168:171], v[56:59]
	v_mfma_f32_16x16x32_bf16 v[52:55], v[160:163], v[168:171], v[52:55]
	v_mfma_f32_16x16x32_bf16 v[40:43], v[152:155], v[176:179], v[40:43]
	v_mfma_f32_16x16x32_bf16 v[36:39], v[160:163], v[176:179], v[36:39]
	v_mfma_f32_16x16x32_bf16 v[24:27], v[152:155], v[184:187], v[24:27]
	v_mfma_f32_16x16x32_bf16 v[20:23], v[160:163], v[184:187], v[20:23]
	v_mfma_f32_16x16x32_bf16 v[8:11], v[152:155], v[192:195], v[8:11]
	v_mfma_f32_16x16x32_bf16 v[4:7], v[160:163], v[192:195], v[4:7]
	s_setprio 0
	s_barrier
	s_add_i32 s52, 0, 0x18000
	v_add_u32_e32 v2, s52, v205
	s_add_i32 s53, 0, 0x1c000
	ds_read_b128 v[92:95], v2
	ds_read_b128 v[96:99], v2 offset:1024
	ds_read_b128 v[120:123], v2 offset:2048
	ds_read_b128 v[132:135], v2 offset:3072
	v_add_u32_e32 v2, s53, v205
	ds_read_b128 v[140:143], v2
	ds_read_b128 v[152:155], v2 offset:1024
	ds_read_b128 v[156:159], v2 offset:2048
	ds_read_b128 v[160:163], v2 offset:3072
	s_add_u32 s24, s24, 0x80000
	s_addc_u32 s25, s25, 0
	s_mov_b32 m0, s39
	v_lshl_add_u64 v[210:211], s[24:25], 0, v[196:197]
	ds_read_b128 v[164:167], v215 offset:32768
	ds_read_b128 v[168:171], v215 offset:33792
	ds_read_b128 v[172:175], v215 offset:34816
	ds_read_b128 v[176:179], v215 offset:35840
	ds_read_b128 v[180:183], v215 offset:36864
	ds_read_b128 v[184:187], v215 offset:37888
	ds_read_b128 v[188:191], v215 offset:38912
	ds_read_b128 v[192:195], v215 offset:39936
	global_load_lds_dwordx4 v[210:211], off
	v_lshl_add_u64 v[210:211], s[24:25], 0, v[200:201]
	s_mov_b32 m0, s40
	s_nop 0
	global_load_lds_dwordx4 v[210:211], off
	s_waitcnt vmcnt(8)
	s_waitcnt lgkmcnt(0)
	s_barrier
	s_setprio 1
	s_waitcnt lgkmcnt(0)
	v_mfma_f32_16x16x32_bf16 v[148:151], v[92:95], v[164:167], v[148:151]
	v_mfma_f32_16x16x32_bf16 v[144:147], v[120:123], v[164:167], v[144:147]
	v_mfma_f32_16x16x32_bf16 v[124:127], v[92:95], v[172:175], v[124:127]
	v_mfma_f32_16x16x32_bf16 v[116:119], v[120:123], v[172:175], v[116:119]
	v_mfma_f32_16x16x32_bf16 v[104:107], v[92:95], v[180:183], v[104:107]
	v_mfma_f32_16x16x32_bf16 v[100:103], v[120:123], v[180:183], v[100:103]
	v_mfma_f32_16x16x32_bf16 v[80:83], v[92:95], v[188:191], v[80:83]
	v_mfma_f32_16x16x32_bf16 v[76:79], v[120:123], v[188:191], v[76:79]
	v_mfma_f32_16x16x32_bf16 v[148:151], v[96:99], v[168:171], v[148:151]
	v_mfma_f32_16x16x32_bf16 v[144:147], v[132:135], v[168:171], v[144:147]
	v_mfma_f32_16x16x32_bf16 v[124:127], v[96:99], v[176:179], v[124:127]
	v_mfma_f32_16x16x32_bf16 v[116:119], v[132:135], v[176:179], v[116:119]
	v_mfma_f32_16x16x32_bf16 v[104:107], v[96:99], v[184:187], v[104:107]
	v_mfma_f32_16x16x32_bf16 v[100:103], v[132:135], v[184:187], v[100:103]
	v_mfma_f32_16x16x32_bf16 v[80:83], v[96:99], v[192:195], v[80:83]
	v_mfma_f32_16x16x32_bf16 v[76:79], v[132:135], v[192:195], v[76:79]
	s_setprio 0
	s_setprio 1
	v_mfma_f32_16x16x32_bf16 v[136:139], v[140:143], v[164:167], v[136:139]
	v_mfma_f32_16x16x32_bf16 v[128:131], v[156:159], v[164:167], v[128:131]
	v_mfma_f32_16x16x32_bf16 v[112:115], v[140:143], v[172:175], v[112:115]
	v_mfma_f32_16x16x32_bf16 v[108:111], v[156:159], v[172:175], v[108:111]
	v_mfma_f32_16x16x32_bf16 v[88:91], v[140:143], v[180:183], v[88:91]
	v_mfma_f32_16x16x32_bf16 v[84:87], v[156:159], v[180:183], v[84:87]
	v_mfma_f32_16x16x32_bf16 v[72:75], v[140:143], v[188:191], v[72:75]
	v_mfma_f32_16x16x32_bf16 v[68:71], v[156:159], v[188:191], v[68:71]
	v_mfma_f32_16x16x32_bf16 v[136:139], v[152:155], v[168:171], v[136:139]
	v_mfma_f32_16x16x32_bf16 v[128:131], v[160:163], v[168:171], v[128:131]
	v_mfma_f32_16x16x32_bf16 v[112:115], v[152:155], v[176:179], v[112:115]
	v_mfma_f32_16x16x32_bf16 v[108:111], v[160:163], v[176:179], v[108:111]
	v_mfma_f32_16x16x32_bf16 v[88:91], v[152:155], v[184:187], v[88:91]
	v_mfma_f32_16x16x32_bf16 v[84:87], v[160:163], v[184:187], v[84:87]
	v_mfma_f32_16x16x32_bf16 v[72:75], v[152:155], v[192:195], v[72:75]
	v_mfma_f32_16x16x32_bf16 v[68:71], v[160:163], v[192:195], v[68:71]
	s_setprio 0
	s_barrier
	s_add_u32 s24, s22, 0x8000
	s_addc_u32 s25, s23, 0
	s_add_i32 s52, s52, s37
	v_lshl_add_u64 v[210:211], s[24:25], 0, v[198:199]
	s_mov_b32 m0, s52
	ds_read_b128 v[164:167], v215 offset:49152
	ds_read_b128 v[168:171], v215 offset:50176
	ds_read_b128 v[172:175], v215 offset:51200
	ds_read_b128 v[176:179], v215 offset:52224
	ds_read_b128 v[180:183], v215 offset:53248
	ds_read_b128 v[184:187], v215 offset:54272
	ds_read_b128 v[188:191], v215 offset:55296
	ds_read_b128 v[192:195], v215 offset:56320
	global_load_lds_dwordx4 v[210:211], off
	s_add_i32 m0, s52, 0x2000
	s_add_u32 s22, s22, 0xc000
	v_lshl_add_u64 v[210:211], s[24:25], 0, v[202:203]
	s_addc_u32 s23, s23, 0
	s_add_i32 s24, s53, s37
	global_load_lds_dwordx4 v[210:211], off
	v_lshl_add_u64 v[210:211], s[22:23], 0, v[198:199]
	s_mov_b32 m0, s24
	v_lshl_add_u64 v[206:207], v[206:207], 0, s[74:75]
	global_load_lds_dwordx4 v[210:211], off
	v_lshl_add_u64 v[210:211], s[22:23], 0, v[202:203]
	s_add_i32 m0, s24, 0x2000
	s_nop 0
	global_load_lds_dwordx4 v[210:211], off
	s_mov_b32 m0, s47
	s_nop 0
	global_load_lds_dwordx4 v[206:207], off
	v_lshl_add_u64 v[206:207], v[208:209], 0, s[74:75]
	s_mov_b32 m0, s48
	s_nop 0
	global_load_lds_dwordx4 v[206:207], off
	s_waitcnt vmcnt(8)
	s_waitcnt lgkmcnt(0)
	s_barrier
	s_setprio 1
	s_waitcnt lgkmcnt(0)
	v_mfma_f32_16x16x32_bf16 v[64:67], v[92:95], v[164:167], v[64:67]
	v_mfma_f32_16x16x32_bf16 v[60:63], v[120:123], v[164:167], v[60:63]
	v_mfma_f32_16x16x32_bf16 v[48:51], v[92:95], v[172:175], v[48:51]
	v_mfma_f32_16x16x32_bf16 v[44:47], v[120:123], v[172:175], v[44:47]
	v_mfma_f32_16x16x32_bf16 v[32:35], v[92:95], v[180:183], v[32:35]
	v_mfma_f32_16x16x32_bf16 v[28:31], v[120:123], v[180:183], v[28:31]
	v_mfma_f32_16x16x32_bf16 v[16:19], v[92:95], v[188:191], v[16:19]
	v_mfma_f32_16x16x32_bf16 v[12:15], v[120:123], v[188:191], v[12:15]
	v_mfma_f32_16x16x32_bf16 v[64:67], v[96:99], v[168:171], v[64:67]
	v_mfma_f32_16x16x32_bf16 v[60:63], v[132:135], v[168:171], v[60:63]
	v_mfma_f32_16x16x32_bf16 v[48:51], v[96:99], v[176:179], v[48:51]
	v_mfma_f32_16x16x32_bf16 v[44:47], v[132:135], v[176:179], v[44:47]
	v_mfma_f32_16x16x32_bf16 v[32:35], v[96:99], v[184:187], v[32:35]
	v_mfma_f32_16x16x32_bf16 v[28:31], v[132:135], v[184:187], v[28:31]
	v_mfma_f32_16x16x32_bf16 v[16:19], v[96:99], v[192:195], v[16:19]
	v_mfma_f32_16x16x32_bf16 v[12:15], v[132:135], v[192:195], v[12:15]
	s_setprio 0
	s_setprio 1
	v_mfma_f32_16x16x32_bf16 v[56:59], v[140:143], v[164:167], v[56:59]
	v_mfma_f32_16x16x32_bf16 v[52:55], v[156:159], v[164:167], v[52:55]
	v_mfma_f32_16x16x32_bf16 v[40:43], v[140:143], v[172:175], v[40:43]
	v_mfma_f32_16x16x32_bf16 v[36:39], v[156:159], v[172:175], v[36:39]
	v_mfma_f32_16x16x32_bf16 v[24:27], v[140:143], v[180:183], v[24:27]
	v_mfma_f32_16x16x32_bf16 v[20:23], v[156:159], v[180:183], v[20:23]
	v_mfma_f32_16x16x32_bf16 v[8:11], v[140:143], v[188:191], v[8:11]
	v_mfma_f32_16x16x32_bf16 v[4:7], v[156:159], v[188:191], v[4:7]
	v_mfma_f32_16x16x32_bf16 v[56:59], v[152:155], v[168:171], v[56:59]
	v_mfma_f32_16x16x32_bf16 v[52:55], v[160:163], v[168:171], v[52:55]
	v_mfma_f32_16x16x32_bf16 v[40:43], v[152:155], v[176:179], v[40:43]
	v_mfma_f32_16x16x32_bf16 v[36:39], v[160:163], v[176:179], v[36:39]
	v_mfma_f32_16x16x32_bf16 v[24:27], v[152:155], v[184:187], v[24:27]
	v_mfma_f32_16x16x32_bf16 v[20:23], v[160:163], v[184:187], v[20:23]
	v_mfma_f32_16x16x32_bf16 v[8:11], v[152:155], v[192:195], v[8:11]
	v_mfma_f32_16x16x32_bf16 v[4:7], v[160:163], v[192:195], v[4:7]
	s_setprio 0
	s_barrier
	s_add_i32 s51, s51, 2
	s_add_u32 s27, s27, 0x10000
	s_addc_u32 s50, s50, 0
	s_add_u32 s12, s12, 0x100
	s_addc_u32 s13, s13, 0
	s_cmp_gt_u32 s51, 29
	.p2align	6

.LBB0_493:
	s_nop 8
	v_sub_f32_e32 v20, v20, v205
	v_sub_f32_e32 v4, v4, v205
	v_exp_f32_e32 v68, v20
	v_sub_f32_e32 v20, v21, v205
	v_exp_f32_e32 v84, v4
	v_sub_f32_e32 v4, v5, v205
	s_xor_b64 s[24:25], s[6:7], -1
	v_exp_f32_e32 v69, v20
	v_sub_f32_e32 v20, v22, v205
	v_exp_f32_e32 v85, v4
	v_sub_f32_e32 v4, v6, v205
	s_mov_b64 s[6:7], 0x18000
	s_cmp_lg_u32 0, -1
	v_exp_f32_e32 v70, v20
	v_sub_f32_e32 v20, v23, v205
	v_exp_f32_e32 v86, v4
	v_sub_f32_e32 v4, v7, v205
	s_waitcnt vmcnt(0) lgkmcnt(0)
	s_barrier
	v_lshl_add_u64 v[36:37], v[36:37], 0, s[6:7]
	s_cselect_b32 s7, 0, 0
	v_exp_f32_e32 v71, v20
	v_sub_f32_e32 v20, v24, v205
	v_exp_f32_e32 v87, v4
	v_sub_f32_e32 v4, v8, v205
	s_mov_b32 s6, m0
	s_mov_b32 m0, s31
	s_nop 0
	global_load_lds_dwordx4 v[36:37], off
	s_mov_b32 m0, s6
	s_add_i32 s7, s7, s30
	v_exp_f32_e32 v72, v20
	v_sub_f32_e32 v20, v25, v205
	v_exp_f32_e32 v88, v4
	v_sub_f32_e32 v4, v9, v205
	v_lshl_add_u64 v[36:37], v[38:39], 0, s[58:59]
	s_add_i32 s10, s7, 0xa000
	s_mov_b32 s11, m0
	s_mov_b32 m0, s10
	s_nop 0
	global_load_lds_dwordx4 v[36:37], off
	s_mov_b32 m0, s11
	v_exp_f32_e32 v73, v20
	v_sub_f32_e32 v20, v26, v205
	v_exp_f32_e32 v89, v4
	v_sub_f32_e32 v4, v10, v205
	s_mov_b64 s[10:11], 0x8080
	v_exp_f32_e32 v74, v20
	v_sub_f32_e32 v20, v27, v205
	v_exp_f32_e32 v90, v4
	v_sub_f32_e32 v4, v11, v205
	v_lshl_add_u64 v[36:37], v[38:39], 0, s[10:11]
	s_add_i32 s7, s7, 0xc000
	s_mov_b32 s10, m0
	s_mov_b32 m0, s7
	s_nop 0
	global_load_lds_dwordx4 v[36:37], off
	s_mov_b32 m0, s10
	v_exp_f32_e32 v75, v20
	v_sub_f32_e32 v20, v28, v205
	v_exp_f32_e32 v91, v4
	v_sub_f32_e32 v4, v12, v205
	ds_read_b128 v[192:195], v251 offset:8192
	ds_read_b128 v[188:191], v251 offset:8704
	ds_read_b128 v[184:187], v251 offset:10240
	ds_read_b128 v[180:183], v251 offset:10752
	ds_read_b128 v[176:179], v251 offset:12288
	ds_read_b128 v[172:175], v251 offset:12800
	ds_read_b128 v[168:171], v251 offset:14336
	ds_read_b128 v[164:167], v251 offset:14848
	v_exp_f32_e32 v76, v20
	v_sub_f32_e32 v20, v29, v205
	v_exp_f32_e32 v92, v4
	v_sub_f32_e32 v4, v13, v205
	v_exp_f32_e32 v77, v20
	v_sub_f32_e32 v20, v30, v205
	v_exp_f32_e32 v93, v4
	v_sub_f32_e32 v4, v14, v205
	v_exp_f32_e32 v78, v20
	v_sub_f32_e32 v20, v31, v205
	v_exp_f32_e32 v94, v4
	v_sub_f32_e32 v4, v15, v205
	v_exp_f32_e32 v79, v20
	v_sub_f32_e32 v20, v32, v205
	v_exp_f32_e32 v95, v4
	v_sub_f32_e32 v4, v16, v205
	v_exp_f32_e32 v80, v20
	v_sub_f32_e32 v20, v33, v205
	v_exp_f32_e32 v96, v4
	v_sub_f32_e32 v4, v17, v205
	v_exp_f32_e32 v81, v20
	v_sub_f32_e32 v20, v34, v205
	v_exp_f32_e32 v97, v4
	v_sub_f32_e32 v4, v18, v205
	v_exp_f32_e32 v82, v20
	v_sub_f32_e32 v20, v35, v205
	v_exp_f32_e32 v98, v4
	v_sub_f32_e32 v4, v19, v205
	v_exp_f32_e32 v83, v20
	v_exp_f32_e32 v99, v4
	s_waitcnt vmcnt(3) lgkmcnt(0)
	s_barrier
	v_mov_b32_e32 v52, v3
	v_mov_b32_e32 v53, v3
	s_add_i32 s72, s35, s12
	v_mov_b32_e32 v54, v3
	v_mov_b32_e32 v55, v3
	v_mov_b32_e32 v56, v3
	v_mov_b32_e32 v57, v3
	v_mov_b32_e32 v58, v3
	v_mov_b32_e32 v59, v3
	v_mov_b32_e32 v60, v3
	v_mov_b32_e32 v61, v3
	v_mov_b32_e32 v62, v3
	v_mov_b32_e32 v63, v3
	v_mov_b32_e32 v64, v3
	v_mov_b32_e32 v65, v3
	v_mov_b32_e32 v66, v3
	v_mov_b32_e32 v67, v3
	v_mov_b64_e32 v[36:37], v[52:53]
	v_mov_b64_e32 v[20:21], v[52:53]
	v_mov_b64_e32 v[4:5], v[52:53]
	s_mov_b32 s6, 0
	v_lshl_add_u64 v[200:201], s[72:73], 1, v[226:227]
	s_movk_i32 s26, 0x4000
	s_movk_i32 s38, 0x2000
	v_mov_b32_e32 v229, 0
	s_mov_b32 s27, 6
	s_mov_b32 s39, 7
	s_mov_b32 s40, 5
	v_mov_b64_e32 v[202:203], v[224:225]
	v_mov_b64_e32 v[38:39], v[54:55]
	v_mov_b64_e32 v[40:41], v[56:57]
	v_mov_b64_e32 v[42:43], v[58:59]
	v_mov_b64_e32 v[44:45], v[60:61]
	v_mov_b64_e32 v[46:47], v[62:63]
	v_mov_b64_e32 v[48:49], v[64:65]
	v_mov_b64_e32 v[50:51], v[66:67]
	v_mov_b64_e32 v[22:23], v[54:55]
	v_mov_b64_e32 v[24:25], v[56:57]
	v_mov_b64_e32 v[26:27], v[58:59]
	v_mov_b64_e32 v[28:29], v[60:61]
	v_mov_b64_e32 v[30:31], v[62:63]
	v_mov_b64_e32 v[32:33], v[64:65]
	v_mov_b64_e32 v[34:35], v[66:67]
	v_mov_b64_e32 v[6:7], v[54:55]
	v_mov_b64_e32 v[8:9], v[56:57]
	v_mov_b64_e32 v[10:11], v[58:59]
	v_mov_b64_e32 v[12:13], v[60:61]
	v_mov_b64_e32 v[14:15], v[62:63]
	v_mov_b64_e32 v[16:17], v[64:65]
	v_mov_b64_e32 v[18:19], v[66:67]
	.p2align	6

.LBB0_639:
	s_ashr_i32 s5, s4, 31
	s_lshl_b64 s[24:25], s[4:5], 20
	v_readlane_b32 s5, v254, 27
	s_add_u32 s36, s5, s24
	s_addc_u32 s37, s33, s25
	s_and_b64 s[24:25], s[16:17], exec
	s_cselect_b32 s5, s37, s23
	s_cselect_b32 s19, s36, s22
	s_ashr_i32 s49, s48, 31
	s_lshl_b64 s[24:25], s[48:49], 20
	v_readlane_b32 s26, v254, 46
	s_add_u32 s42, s26, s24
	v_readlane_b32 s24, v254, 48
	s_addc_u32 s43, s24, s25
	s_and_b64 s[24:25], s[16:17], exec
	s_cselect_b32 s26, s43, s21
	s_cselect_b32 s27, s42, s20
	s_add_u32 s29, s20, 0x10000
	s_addc_u32 s49, s21, 0
	s_add_u32 s20, s22, 0x80080
	s_addc_u32 s21, s23, 0
	s_mov_b32 s54, -2
	s_add_u32 s22, s20, 0xfff80080
	s_addc_u32 s23, s21, -1
	s_add_i32 s55, 0, 0x10000
	s_cmp_eq_u32 s54, 28
	s_cselect_b32 s25, s5, s23
	s_cselect_b32 s24, s19, s22
	s_cselect_b32 s23, s26, s49
	s_cselect_b32 s22, s27, s29
	s_add_i32 s63, 0, 0x14000
	v_add_u32_e32 v144, s55, v178
	v_add_u32_e32 v160, s63, v178
	ds_read_b128 v[132:135], v144
	ds_read_b128 v[136:139], v144 offset:1024
	ds_read_b128 v[140:143], v144 offset:2048
	ds_read_b128 v[144:147], v144 offset:3072
	ds_read_b128 v[148:151], v160
	ds_read_b128 v[152:155], v160 offset:1024
	ds_read_b128 v[156:159], v160 offset:2048
	ds_read_b128 v[160:163], v160 offset:3072
	v_lshl_add_u64 v[206:207], s[20:21], 0, v[170:171]
	s_add_i32 m0, s39, 0xc000
	ds_read_b128 v[174:177], v186
	ds_read_b128 v[190:193], v186 offset:1024
	ds_read_b128 v[194:197], v186 offset:2048
	ds_read_b128 v[198:201], v186 offset:3072
	ds_read_b128 v[202:205], v186 offset:4096
	ds_read_b128 v[214:217], v186 offset:5120
	ds_read_b128 v[218:221], v186 offset:6144
	ds_read_b128 v[222:225], v186 offset:7168
	global_load_lds_dwordx4 v[206:207], off
	v_lshl_add_u64 v[206:207], s[20:21], 0, v[172:173]
	s_add_i32 m0, s39, 0xe000
	s_nop 0
	global_load_lds_dwordx4 v[206:207], off
	s_waitcnt vmcnt(8)
	s_waitcnt lgkmcnt(0)
	s_barrier
	s_setprio 1
	s_waitcnt lgkmcnt(0)
	v_mfma_f32_16x16x32_bf16 v[128:131], v[132:135], v[174:177], 0
	v_mfma_f32_16x16x32_bf16 v[124:127], v[140:143], v[174:177], 0
	v_mfma_f32_16x16x32_bf16 v[108:111], v[132:135], v[194:197], 0
	v_mfma_f32_16x16x32_bf16 v[116:119], v[140:143], v[194:197], 0
	v_mfma_f32_16x16x32_bf16 v[92:95], v[132:135], v[202:205], 0
	v_mfma_f32_16x16x32_bf16 v[88:91], v[140:143], v[202:205], 0
	v_mfma_f32_16x16x32_bf16 v[76:79], v[132:135], v[218:221], 0
	v_mfma_f32_16x16x32_bf16 v[80:83], v[140:143], v[218:221], 0
	v_mfma_f32_16x16x32_bf16 v[128:131], v[136:139], v[190:193], v[128:131]
	v_mfma_f32_16x16x32_bf16 v[124:127], v[144:147], v[190:193], v[124:127]
	v_mfma_f32_16x16x32_bf16 v[108:111], v[136:139], v[198:201], v[108:111]
	v_mfma_f32_16x16x32_bf16 v[116:119], v[144:147], v[198:201], v[116:119]
	v_mfma_f32_16x16x32_bf16 v[92:95], v[136:139], v[214:217], v[92:95]
	v_mfma_f32_16x16x32_bf16 v[88:91], v[144:147], v[214:217], v[88:91]
	v_mfma_f32_16x16x32_bf16 v[76:79], v[136:139], v[222:225], v[76:79]
	v_mfma_f32_16x16x32_bf16 v[80:83], v[144:147], v[222:225], v[80:83]
	s_setprio 0
	s_setprio 1
	v_mfma_f32_16x16x32_bf16 v[120:123], v[148:151], v[174:177], 0
	v_mfma_f32_16x16x32_bf16 v[104:107], v[156:159], v[174:177], 0
	v_mfma_f32_16x16x32_bf16 v[100:103], v[148:151], v[194:197], 0
	v_mfma_f32_16x16x32_bf16 v[96:99], v[156:159], v[194:197], 0
	v_mfma_f32_16x16x32_bf16 v[84:87], v[148:151], v[202:205], 0
	v_mfma_f32_16x16x32_bf16 v[72:75], v[156:159], v[202:205], 0
	v_mfma_f32_16x16x32_bf16 v[68:71], v[148:151], v[218:221], 0
	v_mfma_f32_16x16x32_bf16 v[64:67], v[156:159], v[218:221], 0
	v_mfma_f32_16x16x32_bf16 v[120:123], v[152:155], v[190:193], v[120:123]
	v_mfma_f32_16x16x32_bf16 v[104:107], v[160:163], v[190:193], v[104:107]
	v_mfma_f32_16x16x32_bf16 v[100:103], v[152:155], v[198:201], v[100:103]
	v_mfma_f32_16x16x32_bf16 v[96:99], v[160:163], v[198:201], v[96:99]
	v_mfma_f32_16x16x32_bf16 v[84:87], v[152:155], v[214:217], v[84:87]
	v_mfma_f32_16x16x32_bf16 v[72:75], v[160:163], v[214:217], v[72:75]
	v_mfma_f32_16x16x32_bf16 v[68:71], v[152:155], v[222:225], v[68:71]
	v_mfma_f32_16x16x32_bf16 v[64:67], v[160:163], v[222:225], v[64:67]
	s_setprio 0
	s_barrier
	s_add_i32 s55, s55, s38
	v_lshl_add_u64 v[206:207], s[22:23], 0, v[164:165]
	s_mov_b32 m0, s55
	ds_read_b128 v[174:177], v186 offset:16384
	ds_read_b128 v[190:193], v186 offset:17408
	ds_read_b128 v[194:197], v186 offset:18432
	ds_read_b128 v[198:201], v186 offset:19456
	ds_read_b128 v[202:205], v186 offset:20480
	ds_read_b128 v[214:217], v186 offset:21504
	ds_read_b128 v[218:221], v186 offset:22528
	ds_read_b128 v[222:225], v186 offset:23552
	global_load_lds_dwordx4 v[206:207], off
	s_add_i32 m0, s55, 0x2000
	s_add_u32 s60, s22, 0x4000
	v_lshl_add_u64 v[206:207], s[22:23], 0, v[168:169]
	s_addc_u32 s61, s23, 0
	s_add_i32 s55, s63, s38
	global_load_lds_dwordx4 v[206:207], off
	v_lshl_add_u64 v[206:207], s[60:61], 0, v[164:165]
	s_mov_b32 m0, s55
	v_lshl_add_u64 v[208:209], s[24:25], 0, v[166:167]
	global_load_lds_dwordx4 v[206:207], off
	v_lshl_add_u64 v[206:207], s[60:61], 0, v[168:169]
	s_add_i32 m0, s55, 0x2000
	s_nop 0
	global_load_lds_dwordx4 v[206:207], off
	v_lshl_add_u64 v[206:207], s[24:25], 0, v[2:3]
	s_mov_b32 m0, s39
	s_nop 0
	global_load_lds_dwordx4 v[206:207], off
	s_mov_b32 m0, s44
	s_nop 0
	global_load_lds_dwordx4 v[208:209], off
	s_waitcnt vmcnt(8)
	s_waitcnt lgkmcnt(0)
	s_barrier
	s_setprio 1
	s_waitcnt lgkmcnt(0)
	v_mfma_f32_16x16x32_bf16 v[60:63], v[132:135], v[174:177], 0
	v_mfma_f32_16x16x32_bf16 v[56:59], v[140:143], v[174:177], 0
	v_mfma_f32_16x16x32_bf16 v[44:47], v[132:135], v[194:197], 0
	v_mfma_f32_16x16x32_bf16 v[48:51], v[140:143], v[194:197], 0
	v_mfma_f32_16x16x32_bf16 v[28:31], v[132:135], v[202:205], 0
	v_mfma_f32_16x16x32_bf16 v[24:27], v[140:143], v[202:205], 0
	v_mfma_f32_16x16x32_bf16 v[112:115], v[132:135], v[218:221], 0
	v_mfma_f32_16x16x32_bf16 v[16:19], v[140:143], v[218:221], 0
	v_mfma_f32_16x16x32_bf16 v[60:63], v[136:139], v[190:193], v[60:63]
	v_mfma_f32_16x16x32_bf16 v[56:59], v[144:147], v[190:193], v[56:59]
	v_mfma_f32_16x16x32_bf16 v[44:47], v[136:139], v[198:201], v[44:47]
	v_mfma_f32_16x16x32_bf16 v[48:51], v[144:147], v[198:201], v[48:51]
	v_mfma_f32_16x16x32_bf16 v[28:31], v[136:139], v[214:217], v[28:31]
	v_mfma_f32_16x16x32_bf16 v[24:27], v[144:147], v[214:217], v[24:27]
	v_mfma_f32_16x16x32_bf16 v[112:115], v[136:139], v[222:225], v[112:115]
	v_mfma_f32_16x16x32_bf16 v[16:19], v[144:147], v[222:225], v[16:19]
	s_setprio 0
	s_setprio 1
	v_mfma_f32_16x16x32_bf16 v[52:55], v[148:151], v[174:177], 0
	v_mfma_f32_16x16x32_bf16 v[40:43], v[156:159], v[174:177], 0
	v_mfma_f32_16x16x32_bf16 v[36:39], v[148:151], v[194:197], 0
	v_mfma_f32_16x16x32_bf16 v[32:35], v[156:159], v[194:197], 0
	v_mfma_f32_16x16x32_bf16 v[20:23], v[148:151], v[202:205], 0
	v_mfma_f32_16x16x32_bf16 v[12:15], v[156:159], v[202:205], 0
	v_mfma_f32_16x16x32_bf16 v[4:7], v[148:151], v[218:221], 0
	v_mfma_f32_16x16x32_bf16 v[8:11], v[156:159], v[218:221], 0
	v_mfma_f32_16x16x32_bf16 v[52:55], v[152:155], v[190:193], v[52:55]
	v_mfma_f32_16x16x32_bf16 v[40:43], v[160:163], v[190:193], v[40:43]
	v_mfma_f32_16x16x32_bf16 v[36:39], v[152:155], v[198:201], v[36:39]
	v_mfma_f32_16x16x32_bf16 v[32:35], v[160:163], v[198:201], v[32:35]
	v_mfma_f32_16x16x32_bf16 v[20:23], v[152:155], v[214:217], v[20:23]
	v_mfma_f32_16x16x32_bf16 v[12:15], v[160:163], v[214:217], v[12:15]
	v_mfma_f32_16x16x32_bf16 v[4:7], v[152:155], v[222:225], v[4:7]
	v_mfma_f32_16x16x32_bf16 v[8:11], v[160:163], v[222:225], v[8:11]
	s_setprio 0
	s_barrier
	s_add_i32 s55, 0, 0x18000
	s_add_i32 s60, 0, 0x1c000
	v_add_u32_e32 v144, s55, v178
	v_add_u32_e32 v160, s60, v178
	ds_read_b128 v[132:135], v144
	ds_read_b128 v[136:139], v144 offset:1024
	ds_read_b128 v[140:143], v144 offset:2048
	ds_read_b128 v[144:147], v144 offset:3072
	ds_read_b128 v[148:151], v160
	ds_read_b128 v[152:155], v160 offset:1024
	ds_read_b128 v[156:159], v160 offset:2048
	ds_read_b128 v[160:163], v160 offset:3072
	s_add_u32 s24, s24, 0x80000
	s_addc_u32 s25, s25, 0
	s_mov_b32 m0, s45
	v_lshl_add_u64 v[210:211], s[24:25], 0, v[2:3]
	ds_read_b128 v[174:177], v186 offset:32768
	ds_read_b128 v[190:193], v186 offset:33792
	ds_read_b128 v[194:197], v186 offset:34816
	ds_read_b128 v[198:201], v186 offset:35840
	ds_read_b128 v[202:205], v186 offset:36864
	ds_read_b128 v[214:217], v186 offset:37888
	ds_read_b128 v[218:221], v186 offset:38912
	ds_read_b128 v[222:225], v186 offset:39936
	global_load_lds_dwordx4 v[210:211], off
	v_lshl_add_u64 v[210:211], s[24:25], 0, v[166:167]
	s_mov_b32 m0, s50
	s_nop 0
	global_load_lds_dwordx4 v[210:211], off
	s_waitcnt vmcnt(8)
	s_waitcnt lgkmcnt(0)
	s_barrier
	s_setprio 1
	s_waitcnt lgkmcnt(0)
	v_mfma_f32_16x16x32_bf16 v[128:131], v[132:135], v[174:177], v[128:131]
	v_mfma_f32_16x16x32_bf16 v[124:127], v[140:143], v[174:177], v[124:127]
	v_mfma_f32_16x16x32_bf16 v[108:111], v[132:135], v[194:197], v[108:111]
	v_mfma_f32_16x16x32_bf16 v[116:119], v[140:143], v[194:197], v[116:119]
	v_mfma_f32_16x16x32_bf16 v[92:95], v[132:135], v[202:205], v[92:95]
	v_mfma_f32_16x16x32_bf16 v[88:91], v[140:143], v[202:205], v[88:91]
	v_mfma_f32_16x16x32_bf16 v[76:79], v[132:135], v[218:221], v[76:79]
	v_mfma_f32_16x16x32_bf16 v[80:83], v[140:143], v[218:221], v[80:83]
	v_mfma_f32_16x16x32_bf16 v[128:131], v[136:139], v[190:193], v[128:131]
	v_mfma_f32_16x16x32_bf16 v[124:127], v[144:147], v[190:193], v[124:127]
	v_mfma_f32_16x16x32_bf16 v[108:111], v[136:139], v[198:201], v[108:111]
	v_mfma_f32_16x16x32_bf16 v[116:119], v[144:147], v[198:201], v[116:119]
	v_mfma_f32_16x16x32_bf16 v[92:95], v[136:139], v[214:217], v[92:95]
	v_mfma_f32_16x16x32_bf16 v[88:91], v[144:147], v[214:217], v[88:91]
	v_mfma_f32_16x16x32_bf16 v[76:79], v[136:139], v[222:225], v[76:79]
	v_mfma_f32_16x16x32_bf16 v[80:83], v[144:147], v[222:225], v[80:83]
	s_setprio 0
	s_setprio 1
	v_mfma_f32_16x16x32_bf16 v[120:123], v[148:151], v[174:177], v[120:123]
	v_mfma_f32_16x16x32_bf16 v[104:107], v[156:159], v[174:177], v[104:107]
	v_mfma_f32_16x16x32_bf16 v[100:103], v[148:151], v[194:197], v[100:103]
	v_mfma_f32_16x16x32_bf16 v[96:99], v[156:159], v[194:197], v[96:99]
	v_mfma_f32_16x16x32_bf16 v[84:87], v[148:151], v[202:205], v[84:87]
	v_mfma_f32_16x16x32_bf16 v[72:75], v[156:159], v[202:205], v[72:75]
	v_mfma_f32_16x16x32_bf16 v[68:71], v[148:151], v[218:221], v[68:71]
	v_mfma_f32_16x16x32_bf16 v[64:67], v[156:159], v[218:221], v[64:67]
	v_mfma_f32_16x16x32_bf16 v[120:123], v[152:155], v[190:193], v[120:123]
	v_mfma_f32_16x16x32_bf16 v[104:107], v[160:163], v[190:193], v[104:107]
	v_mfma_f32_16x16x32_bf16 v[100:103], v[152:155], v[198:201], v[100:103]
	v_mfma_f32_16x16x32_bf16 v[96:99], v[160:163], v[198:201], v[96:99]
	v_mfma_f32_16x16x32_bf16 v[84:87], v[152:155], v[214:217], v[84:87]
	v_mfma_f32_16x16x32_bf16 v[72:75], v[160:163], v[214:217], v[72:75]
	v_mfma_f32_16x16x32_bf16 v[68:71], v[152:155], v[222:225], v[68:71]
	v_mfma_f32_16x16x32_bf16 v[64:67], v[160:163], v[222:225], v[64:67]
	s_setprio 0
	s_barrier
	s_add_u32 s24, s22, 0x8000
	s_addc_u32 s25, s23, 0
	s_add_i32 s55, s55, s38
	v_lshl_add_u64 v[210:211], s[24:25], 0, v[164:165]
	s_mov_b32 m0, s55
	ds_read_b128 v[174:177], v186 offset:49152
	ds_read_b128 v[190:193], v186 offset:50176
	ds_read_b128 v[194:197], v186 offset:51200
	ds_read_b128 v[198:201], v186 offset:52224
	ds_read_b128 v[202:205], v186 offset:53248
	ds_read_b128 v[214:217], v186 offset:54272
	ds_read_b128 v[218:221], v186 offset:55296
	ds_read_b128 v[222:225], v186 offset:56320
	global_load_lds_dwordx4 v[210:211], off
	s_add_i32 m0, s55, 0x2000
	s_add_u32 s22, s22, 0xc000
	v_lshl_add_u64 v[210:211], s[24:25], 0, v[168:169]
	s_addc_u32 s23, s23, 0
	s_add_i32 s24, s60, s38
	global_load_lds_dwordx4 v[210:211], off
	v_lshl_add_u64 v[210:211], s[22:23], 0, v[164:165]
	s_mov_b32 m0, s24
	v_lshl_add_u64 v[206:207], v[206:207], 0, s[74:75]
	global_load_lds_dwordx4 v[210:211], off
	v_lshl_add_u64 v[210:211], s[22:23], 0, v[168:169]
	s_add_i32 m0, s24, 0x2000
	s_nop 0
	global_load_lds_dwordx4 v[210:211], off
	s_mov_b32 m0, s56
	s_nop 0
	global_load_lds_dwordx4 v[206:207], off
	v_lshl_add_u64 v[206:207], v[208:209], 0, s[74:75]
	s_mov_b32 m0, s57
	s_nop 0
	global_load_lds_dwordx4 v[206:207], off
	s_waitcnt vmcnt(8)
	s_waitcnt lgkmcnt(0)
	s_barrier
	s_setprio 1
	s_waitcnt lgkmcnt(0)
	v_mfma_f32_16x16x32_bf16 v[60:63], v[132:135], v[174:177], v[60:63]
	v_mfma_f32_16x16x32_bf16 v[56:59], v[140:143], v[174:177], v[56:59]
	v_mfma_f32_16x16x32_bf16 v[44:47], v[132:135], v[194:197], v[44:47]
	v_mfma_f32_16x16x32_bf16 v[48:51], v[140:143], v[194:197], v[48:51]
	v_mfma_f32_16x16x32_bf16 v[28:31], v[132:135], v[202:205], v[28:31]
	v_mfma_f32_16x16x32_bf16 v[24:27], v[140:143], v[202:205], v[24:27]
	v_mfma_f32_16x16x32_bf16 v[112:115], v[132:135], v[218:221], v[112:115]
	v_mfma_f32_16x16x32_bf16 v[16:19], v[140:143], v[218:221], v[16:19]
	v_mfma_f32_16x16x32_bf16 v[60:63], v[136:139], v[190:193], v[60:63]
	v_mfma_f32_16x16x32_bf16 v[56:59], v[144:147], v[190:193], v[56:59]
	v_mfma_f32_16x16x32_bf16 v[44:47], v[136:139], v[198:201], v[44:47]
	v_mfma_f32_16x16x32_bf16 v[48:51], v[144:147], v[198:201], v[48:51]
	v_mfma_f32_16x16x32_bf16 v[28:31], v[136:139], v[214:217], v[28:31]
	v_mfma_f32_16x16x32_bf16 v[24:27], v[144:147], v[214:217], v[24:27]
	v_mfma_f32_16x16x32_bf16 v[112:115], v[136:139], v[222:225], v[112:115]
	v_mfma_f32_16x16x32_bf16 v[16:19], v[144:147], v[222:225], v[16:19]
	s_setprio 0
	s_setprio 1
	v_mfma_f32_16x16x32_bf16 v[52:55], v[148:151], v[174:177], v[52:55]
	v_mfma_f32_16x16x32_bf16 v[40:43], v[156:159], v[174:177], v[40:43]
	v_mfma_f32_16x16x32_bf16 v[36:39], v[148:151], v[194:197], v[36:39]
	v_mfma_f32_16x16x32_bf16 v[32:35], v[156:159], v[194:197], v[32:35]
	v_mfma_f32_16x16x32_bf16 v[20:23], v[148:151], v[202:205], v[20:23]
	v_mfma_f32_16x16x32_bf16 v[12:15], v[156:159], v[202:205], v[12:15]
	v_mfma_f32_16x16x32_bf16 v[4:7], v[148:151], v[218:221], v[4:7]
	v_mfma_f32_16x16x32_bf16 v[8:11], v[156:159], v[218:221], v[8:11]
	v_mfma_f32_16x16x32_bf16 v[52:55], v[152:155], v[190:193], v[52:55]
	v_mfma_f32_16x16x32_bf16 v[40:43], v[160:163], v[190:193], v[40:43]
	v_mfma_f32_16x16x32_bf16 v[36:39], v[152:155], v[198:201], v[36:39]
	v_mfma_f32_16x16x32_bf16 v[32:35], v[160:163], v[198:201], v[32:35]
	v_mfma_f32_16x16x32_bf16 v[20:23], v[152:155], v[214:217], v[20:23]
	v_mfma_f32_16x16x32_bf16 v[12:15], v[160:163], v[214:217], v[12:15]
	v_mfma_f32_16x16x32_bf16 v[4:7], v[152:155], v[222:225], v[4:7]
	v_mfma_f32_16x16x32_bf16 v[8:11], v[160:163], v[222:225], v[8:11]
	s_setprio 0
	s_barrier
	s_add_i32 s54, s54, 2
	s_add_u32 s29, s29, 0x10000
	s_addc_u32 s49, s49, 0
	s_add_u32 s20, s20, 0x100
	s_addc_u32 s21, s21, 0
	s_cmp_gt_u32 s54, 29
	.p2align	6

.LBB0_743:
	s_ashr_i32 s7, s6, 31
	s_lshl_b64 s[12:13], s[6:7], 20
	s_add_u32 s12, s25, s12
	s_addc_u32 s13, s26, s13
	s_and_b64 s[14:15], s[8:9], exec
	s_cselect_b32 s7, s13, s19
	s_cselect_b32 s45, s12, s18
	s_ashr_i32 s11, s10, 31
	s_lshl_b64 s[14:15], s[10:11], 20
	s_add_u32 s14, s27, s14
	s_addc_u32 s15, s28, s15
	s_and_b64 s[20:21], s[8:9], exec
	s_cselect_b32 s11, s15, s17
	s_cselect_b32 s46, s14, s16
	s_add_u32 s47, s16, 0x10000
	s_addc_u32 s48, s17, 0
	s_add_u32 s16, s18, 0x80080
	s_addc_u32 s17, s19, 0
	s_mov_b32 s49, -2
	s_add_u32 s18, s16, 0xfff80080
	s_addc_u32 s19, s17, -1
	s_add_i32 s50, 0, 0x10000
	s_cmp_eq_u32 s49, 28
	s_cselect_b32 s21, s7, s19
	s_cselect_b32 s20, s45, s18
	s_cselect_b32 s19, s11, s48
	s_cselect_b32 s18, s46, s47
	s_add_i32 s52, 0, 0x14000
	v_add_u32_e32 v168, s50, v158
	v_add_u32_e32 v184, s52, v158
	ds_read_b128 v[154:157], v168
	ds_read_b128 v[160:163], v168 offset:1024
	ds_read_b128 v[164:167], v168 offset:2048
	ds_read_b128 v[168:171], v168 offset:3072
	ds_read_b128 v[172:175], v184
	ds_read_b128 v[176:179], v184 offset:1024
	ds_read_b128 v[180:183], v184 offset:2048
	ds_read_b128 v[184:187], v184 offset:3072
	v_lshl_add_u64 v[208:209], s[16:17], 0, v[150:151]
	s_add_i32 m0, s30, 0xc000
	ds_read_b128 v[188:191], v159
	ds_read_b128 v[192:195], v159 offset:1024
	ds_read_b128 v[196:199], v159 offset:2048
	ds_read_b128 v[200:203], v159 offset:3072
	ds_read_b128 v[204:207], v159 offset:4096
	ds_read_b128 v[214:217], v159 offset:5120
	ds_read_b128 v[218:221], v159 offset:6144
	ds_read_b128 v[222:225], v159 offset:7168
	global_load_lds_dwordx4 v[208:209], off
	v_lshl_add_u64 v[208:209], s[16:17], 0, v[152:153]
	s_add_i32 m0, s30, 0xe000
	s_nop 0
	global_load_lds_dwordx4 v[208:209], off
	s_waitcnt vmcnt(8)
	s_waitcnt lgkmcnt(0)
	s_barrier
	s_setprio 1
	s_waitcnt lgkmcnt(0)
	v_mfma_f32_16x16x32_bf16 v[128:131], v[154:157], v[188:191], 0
	v_mfma_f32_16x16x32_bf16 v[120:123], v[164:167], v[188:191], 0
	v_mfma_f32_16x16x32_bf16 v[112:115], v[154:157], v[196:199], 0
	v_mfma_f32_16x16x32_bf16 v[104:107], v[164:167], v[196:199], 0
	v_mfma_f32_16x16x32_bf16 v[96:99], v[154:157], v[204:207], 0
	v_mfma_f32_16x16x32_bf16 v[88:91], v[164:167], v[204:207], 0
	v_mfma_f32_16x16x32_bf16 v[80:83], v[154:157], v[218:221], 0
	v_mfma_f32_16x16x32_bf16 v[72:75], v[164:167], v[218:221], 0
	v_mfma_f32_16x16x32_bf16 v[128:131], v[160:163], v[192:195], v[128:131]
	v_mfma_f32_16x16x32_bf16 v[120:123], v[168:171], v[192:195], v[120:123]
	v_mfma_f32_16x16x32_bf16 v[112:115], v[160:163], v[200:203], v[112:115]
	v_mfma_f32_16x16x32_bf16 v[104:107], v[168:171], v[200:203], v[104:107]
	v_mfma_f32_16x16x32_bf16 v[96:99], v[160:163], v[214:217], v[96:99]
	v_mfma_f32_16x16x32_bf16 v[88:91], v[168:171], v[214:217], v[88:91]
	v_mfma_f32_16x16x32_bf16 v[80:83], v[160:163], v[222:225], v[80:83]
	v_mfma_f32_16x16x32_bf16 v[72:75], v[168:171], v[222:225], v[72:75]
	s_setprio 0
	s_setprio 1
	v_mfma_f32_16x16x32_bf16 v[124:127], v[172:175], v[188:191], 0
	v_mfma_f32_16x16x32_bf16 v[116:119], v[180:183], v[188:191], 0
	v_mfma_f32_16x16x32_bf16 v[108:111], v[172:175], v[196:199], 0
	v_mfma_f32_16x16x32_bf16 v[100:103], v[180:183], v[196:199], 0
	v_mfma_f32_16x16x32_bf16 v[92:95], v[172:175], v[204:207], 0
	v_mfma_f32_16x16x32_bf16 v[84:87], v[180:183], v[204:207], 0
	v_mfma_f32_16x16x32_bf16 v[76:79], v[172:175], v[218:221], 0
	v_mfma_f32_16x16x32_bf16 v[68:71], v[180:183], v[218:221], 0
	v_mfma_f32_16x16x32_bf16 v[124:127], v[176:179], v[192:195], v[124:127]
	v_mfma_f32_16x16x32_bf16 v[116:119], v[184:187], v[192:195], v[116:119]
	v_mfma_f32_16x16x32_bf16 v[108:111], v[176:179], v[200:203], v[108:111]
	v_mfma_f32_16x16x32_bf16 v[100:103], v[184:187], v[200:203], v[100:103]
	v_mfma_f32_16x16x32_bf16 v[92:95], v[176:179], v[214:217], v[92:95]
	v_mfma_f32_16x16x32_bf16 v[84:87], v[184:187], v[214:217], v[84:87]
	v_mfma_f32_16x16x32_bf16 v[76:79], v[176:179], v[222:225], v[76:79]
	v_mfma_f32_16x16x32_bf16 v[68:71], v[184:187], v[222:225], v[68:71]
	s_setprio 0
	s_barrier
	s_add_i32 s50, s50, s29
	v_lshl_add_u64 v[208:209], s[18:19], 0, v[136:137]
	s_mov_b32 m0, s50
	ds_read_b128 v[188:191], v159 offset:16384
	ds_read_b128 v[192:195], v159 offset:17408
	ds_read_b128 v[196:199], v159 offset:18432
	ds_read_b128 v[200:203], v159 offset:19456
	ds_read_b128 v[204:207], v159 offset:20480
	ds_read_b128 v[214:217], v159 offset:21504
	ds_read_b128 v[218:221], v159 offset:22528
	ds_read_b128 v[222:225], v159 offset:23552
	global_load_lds_dwordx4 v[208:209], off
	s_add_i32 m0, s50, 0x2000
	s_add_u32 s50, s18, 0x4000
	v_lshl_add_u64 v[208:209], s[18:19], 0, v[132:133]
	s_addc_u32 s51, s19, 0
	s_add_i32 s52, s52, s29
	global_load_lds_dwordx4 v[208:209], off
	v_lshl_add_u64 v[208:209], s[50:51], 0, v[136:137]
	s_mov_b32 m0, s52
	v_lshl_add_u64 v[210:211], s[20:21], 0, v[134:135]
	global_load_lds_dwordx4 v[208:209], off
	v_lshl_add_u64 v[208:209], s[50:51], 0, v[132:133]
	s_add_i32 m0, s52, 0x2000
	s_nop 0
	global_load_lds_dwordx4 v[208:209], off
	v_lshl_add_u64 v[208:209], s[20:21], 0, v[138:139]
	s_mov_b32 m0, s30
	s_nop 0
	global_load_lds_dwordx4 v[208:209], off
	s_mov_b32 m0, s31
	s_nop 0
	global_load_lds_dwordx4 v[210:211], off
	s_waitcnt vmcnt(8)
	s_waitcnt lgkmcnt(0)
	s_barrier
	s_setprio 1
	s_waitcnt lgkmcnt(0)
	v_mfma_f32_16x16x32_bf16 v[64:67], v[154:157], v[188:191], 0
	v_mfma_f32_16x16x32_bf16 v[56:59], v[164:167], v[188:191], 0
	v_mfma_f32_16x16x32_bf16 v[48:51], v[154:157], v[196:199], 0
	v_mfma_f32_16x16x32_bf16 v[40:43], v[164:167], v[196:199], 0
	v_mfma_f32_16x16x32_bf16 v[32:35], v[154:157], v[204:207], 0
	v_mfma_f32_16x16x32_bf16 v[24:27], v[164:167], v[204:207], 0
	v_mfma_f32_16x16x32_bf16 v[16:19], v[154:157], v[218:221], 0
	v_mfma_f32_16x16x32_bf16 v[8:11], v[164:167], v[218:221], 0
	v_mfma_f32_16x16x32_bf16 v[64:67], v[160:163], v[192:195], v[64:67]
	v_mfma_f32_16x16x32_bf16 v[56:59], v[168:171], v[192:195], v[56:59]
	v_mfma_f32_16x16x32_bf16 v[48:51], v[160:163], v[200:203], v[48:51]
	v_mfma_f32_16x16x32_bf16 v[40:43], v[168:171], v[200:203], v[40:43]
	v_mfma_f32_16x16x32_bf16 v[32:35], v[160:163], v[214:217], v[32:35]
	v_mfma_f32_16x16x32_bf16 v[24:27], v[168:171], v[214:217], v[24:27]
	v_mfma_f32_16x16x32_bf16 v[16:19], v[160:163], v[222:225], v[16:19]
	v_mfma_f32_16x16x32_bf16 v[8:11], v[168:171], v[222:225], v[8:11]
	s_setprio 0
	s_setprio 1
	v_mfma_f32_16x16x32_bf16 v[60:63], v[172:175], v[188:191], 0
	v_mfma_f32_16x16x32_bf16 v[52:55], v[180:183], v[188:191], 0
	v_mfma_f32_16x16x32_bf16 v[44:47], v[172:175], v[196:199], 0
	v_mfma_f32_16x16x32_bf16 v[36:39], v[180:183], v[196:199], 0
	v_mfma_f32_16x16x32_bf16 v[28:31], v[172:175], v[204:207], 0
	v_mfma_f32_16x16x32_bf16 v[20:23], v[180:183], v[204:207], 0
	v_mfma_f32_16x16x32_bf16 v[12:15], v[172:175], v[218:221], 0
	v_mfma_f32_16x16x32_bf16 v[4:7], v[180:183], v[218:221], 0
	v_mfma_f32_16x16x32_bf16 v[60:63], v[176:179], v[192:195], v[60:63]
	v_mfma_f32_16x16x32_bf16 v[52:55], v[184:187], v[192:195], v[52:55]
	v_mfma_f32_16x16x32_bf16 v[44:47], v[176:179], v[200:203], v[44:47]
	v_mfma_f32_16x16x32_bf16 v[36:39], v[184:187], v[200:203], v[36:39]
	v_mfma_f32_16x16x32_bf16 v[28:31], v[176:179], v[214:217], v[28:31]
	v_mfma_f32_16x16x32_bf16 v[20:23], v[184:187], v[214:217], v[20:23]
	v_mfma_f32_16x16x32_bf16 v[12:15], v[176:179], v[222:225], v[12:15]
	v_mfma_f32_16x16x32_bf16 v[4:7], v[184:187], v[222:225], v[4:7]
	s_setprio 0
	s_barrier
	s_add_i32 s50, 0, 0x18000
	s_add_i32 s51, 0, 0x1c000
	v_add_u32_e32 v168, s50, v158
	v_add_u32_e32 v184, s51, v158
	ds_read_b128 v[154:157], v168
	ds_read_b128 v[160:163], v168 offset:1024
	ds_read_b128 v[164:167], v168 offset:2048
	ds_read_b128 v[168:171], v168 offset:3072
	ds_read_b128 v[172:175], v184
	ds_read_b128 v[176:179], v184 offset:1024
	ds_read_b128 v[180:183], v184 offset:2048
	ds_read_b128 v[184:187], v184 offset:3072
	s_add_u32 s20, s20, 0x80000
	s_addc_u32 s21, s21, 0
	s_mov_b32 m0, s34
	v_lshl_add_u64 v[226:227], s[20:21], 0, v[138:139]
	ds_read_b128 v[188:191], v159 offset:32768
	ds_read_b128 v[192:195], v159 offset:33792
	ds_read_b128 v[196:199], v159 offset:34816
	ds_read_b128 v[200:203], v159 offset:35840
	ds_read_b128 v[204:207], v159 offset:36864
	ds_read_b128 v[214:217], v159 offset:37888
	ds_read_b128 v[218:221], v159 offset:38912
	ds_read_b128 v[222:225], v159 offset:39936
	global_load_lds_dwordx4 v[226:227], off
	v_lshl_add_u64 v[226:227], s[20:21], 0, v[134:135]
	s_mov_b32 m0, s35
	s_nop 0
	global_load_lds_dwordx4 v[226:227], off
	s_waitcnt vmcnt(8)
	s_waitcnt lgkmcnt(0)
	s_barrier
	s_setprio 1
	s_waitcnt lgkmcnt(0)
	v_mfma_f32_16x16x32_bf16 v[128:131], v[154:157], v[188:191], v[128:131]
	v_mfma_f32_16x16x32_bf16 v[120:123], v[164:167], v[188:191], v[120:123]
	v_mfma_f32_16x16x32_bf16 v[112:115], v[154:157], v[196:199], v[112:115]
	v_mfma_f32_16x16x32_bf16 v[104:107], v[164:167], v[196:199], v[104:107]
	v_mfma_f32_16x16x32_bf16 v[96:99], v[154:157], v[204:207], v[96:99]
	v_mfma_f32_16x16x32_bf16 v[88:91], v[164:167], v[204:207], v[88:91]
	v_mfma_f32_16x16x32_bf16 v[80:83], v[154:157], v[218:221], v[80:83]
	v_mfma_f32_16x16x32_bf16 v[72:75], v[164:167], v[218:221], v[72:75]
	v_mfma_f32_16x16x32_bf16 v[128:131], v[160:163], v[192:195], v[128:131]
	v_mfma_f32_16x16x32_bf16 v[120:123], v[168:171], v[192:195], v[120:123]
	v_mfma_f32_16x16x32_bf16 v[112:115], v[160:163], v[200:203], v[112:115]
	v_mfma_f32_16x16x32_bf16 v[104:107], v[168:171], v[200:203], v[104:107]
	v_mfma_f32_16x16x32_bf16 v[96:99], v[160:163], v[214:217], v[96:99]
	v_mfma_f32_16x16x32_bf16 v[88:91], v[168:171], v[214:217], v[88:91]
	v_mfma_f32_16x16x32_bf16 v[80:83], v[160:163], v[222:225], v[80:83]
	v_mfma_f32_16x16x32_bf16 v[72:75], v[168:171], v[222:225], v[72:75]
	s_setprio 0
	s_setprio 1
	v_mfma_f32_16x16x32_bf16 v[124:127], v[172:175], v[188:191], v[124:127]
	v_mfma_f32_16x16x32_bf16 v[116:119], v[180:183], v[188:191], v[116:119]
	v_mfma_f32_16x16x32_bf16 v[108:111], v[172:175], v[196:199], v[108:111]
	v_mfma_f32_16x16x32_bf16 v[100:103], v[180:183], v[196:199], v[100:103]
	v_mfma_f32_16x16x32_bf16 v[92:95], v[172:175], v[204:207], v[92:95]
	v_mfma_f32_16x16x32_bf16 v[84:87], v[180:183], v[204:207], v[84:87]
	v_mfma_f32_16x16x32_bf16 v[76:79], v[172:175], v[218:221], v[76:79]
	v_mfma_f32_16x16x32_bf16 v[68:71], v[180:183], v[218:221], v[68:71]
	v_mfma_f32_16x16x32_bf16 v[124:127], v[176:179], v[192:195], v[124:127]
	v_mfma_f32_16x16x32_bf16 v[116:119], v[184:187], v[192:195], v[116:119]
	v_mfma_f32_16x16x32_bf16 v[108:111], v[176:179], v[200:203], v[108:111]
	v_mfma_f32_16x16x32_bf16 v[100:103], v[184:187], v[200:203], v[100:103]
	v_mfma_f32_16x16x32_bf16 v[92:95], v[176:179], v[214:217], v[92:95]
	v_mfma_f32_16x16x32_bf16 v[84:87], v[184:187], v[214:217], v[84:87]
	v_mfma_f32_16x16x32_bf16 v[76:79], v[176:179], v[222:225], v[76:79]
	v_mfma_f32_16x16x32_bf16 v[68:71], v[184:187], v[222:225], v[68:71]
	s_setprio 0
	s_barrier
	s_add_u32 s20, s18, 0x8000
	s_addc_u32 s21, s19, 0
	s_add_i32 s50, s50, s29
	v_lshl_add_u64 v[226:227], s[20:21], 0, v[136:137]
	s_mov_b32 m0, s50
	ds_read_b128 v[188:191], v159 offset:49152
	ds_read_b128 v[192:195], v159 offset:50176
	ds_read_b128 v[196:199], v159 offset:51200
	ds_read_b128 v[200:203], v159 offset:52224
	ds_read_b128 v[204:207], v159 offset:53248
	ds_read_b128 v[214:217], v159 offset:54272
	ds_read_b128 v[218:221], v159 offset:55296
	ds_read_b128 v[222:225], v159 offset:56320
	global_load_lds_dwordx4 v[226:227], off
	s_add_i32 m0, s50, 0x2000
	s_add_u32 s18, s18, 0xc000
	v_lshl_add_u64 v[226:227], s[20:21], 0, v[132:133]
	s_addc_u32 s19, s19, 0
	s_add_i32 s20, s51, s29
	global_load_lds_dwordx4 v[226:227], off
	v_lshl_add_u64 v[226:227], s[18:19], 0, v[136:137]
	s_mov_b32 m0, s20
	v_lshl_add_u64 v[208:209], v[208:209], 0, s[74:75]
	global_load_lds_dwordx4 v[226:227], off
	v_lshl_add_u64 v[226:227], s[18:19], 0, v[132:133]
	s_add_i32 m0, s20, 0x2000
	s_nop 0
	global_load_lds_dwordx4 v[226:227], off
	s_mov_b32 m0, s39
	s_nop 0
	global_load_lds_dwordx4 v[208:209], off
	v_lshl_add_u64 v[208:209], v[210:211], 0, s[74:75]
	s_mov_b32 m0, s40
	s_nop 0
	global_load_lds_dwordx4 v[208:209], off
	s_waitcnt vmcnt(8)
	s_waitcnt lgkmcnt(0)
	s_barrier
	s_setprio 1
	s_waitcnt lgkmcnt(0)
	v_mfma_f32_16x16x32_bf16 v[64:67], v[154:157], v[188:191], v[64:67]
	v_mfma_f32_16x16x32_bf16 v[56:59], v[164:167], v[188:191], v[56:59]
	v_mfma_f32_16x16x32_bf16 v[48:51], v[154:157], v[196:199], v[48:51]
	v_mfma_f32_16x16x32_bf16 v[40:43], v[164:167], v[196:199], v[40:43]
	v_mfma_f32_16x16x32_bf16 v[32:35], v[154:157], v[204:207], v[32:35]
	v_mfma_f32_16x16x32_bf16 v[24:27], v[164:167], v[204:207], v[24:27]
	v_mfma_f32_16x16x32_bf16 v[16:19], v[154:157], v[218:221], v[16:19]
	v_mfma_f32_16x16x32_bf16 v[8:11], v[164:167], v[218:221], v[8:11]
	v_mfma_f32_16x16x32_bf16 v[64:67], v[160:163], v[192:195], v[64:67]
	v_mfma_f32_16x16x32_bf16 v[56:59], v[168:171], v[192:195], v[56:59]
	v_mfma_f32_16x16x32_bf16 v[48:51], v[160:163], v[200:203], v[48:51]
	v_mfma_f32_16x16x32_bf16 v[40:43], v[168:171], v[200:203], v[40:43]
	v_mfma_f32_16x16x32_bf16 v[32:35], v[160:163], v[214:217], v[32:35]
	v_mfma_f32_16x16x32_bf16 v[24:27], v[168:171], v[214:217], v[24:27]
	v_mfma_f32_16x16x32_bf16 v[16:19], v[160:163], v[222:225], v[16:19]
	v_mfma_f32_16x16x32_bf16 v[8:11], v[168:171], v[222:225], v[8:11]
	s_setprio 0
	s_setprio 1
	v_mfma_f32_16x16x32_bf16 v[60:63], v[172:175], v[188:191], v[60:63]
	v_mfma_f32_16x16x32_bf16 v[52:55], v[180:183], v[188:191], v[52:55]
	v_mfma_f32_16x16x32_bf16 v[44:47], v[172:175], v[196:199], v[44:47]
	v_mfma_f32_16x16x32_bf16 v[36:39], v[180:183], v[196:199], v[36:39]
	v_mfma_f32_16x16x32_bf16 v[28:31], v[172:175], v[204:207], v[28:31]
	v_mfma_f32_16x16x32_bf16 v[20:23], v[180:183], v[204:207], v[20:23]
	v_mfma_f32_16x16x32_bf16 v[12:15], v[172:175], v[218:221], v[12:15]
	v_mfma_f32_16x16x32_bf16 v[4:7], v[180:183], v[218:221], v[4:7]
	v_mfma_f32_16x16x32_bf16 v[60:63], v[176:179], v[192:195], v[60:63]
	v_mfma_f32_16x16x32_bf16 v[52:55], v[184:187], v[192:195], v[52:55]
	v_mfma_f32_16x16x32_bf16 v[44:47], v[176:179], v[200:203], v[44:47]
	v_mfma_f32_16x16x32_bf16 v[36:39], v[184:187], v[200:203], v[36:39]
	v_mfma_f32_16x16x32_bf16 v[28:31], v[176:179], v[214:217], v[28:31]
	v_mfma_f32_16x16x32_bf16 v[20:23], v[184:187], v[214:217], v[20:23]
	v_mfma_f32_16x16x32_bf16 v[12:15], v[176:179], v[222:225], v[12:15]
	v_mfma_f32_16x16x32_bf16 v[4:7], v[184:187], v[222:225], v[4:7]
	s_setprio 0
	s_barrier
	s_add_i32 s49, s49, 2
	s_add_u32 s47, s47, 0x10000
	s_addc_u32 s48, s48, 0
	s_add_u32 s16, s16, 0x100
	s_addc_u32 s17, s17, 0
	s_cmp_gt_u32 s49, 29
	.p2align	6

.LBB0_809:
	s_add_u32 s18, s22, 0xc000
	s_addc_u32 s19, s23, 0
	s_add_u32 s6, s20, 0x10000
	s_addc_u32 s7, s21, 0
	s_mov_b32 s26, -2
	s_add_u32 s20, s18, 0x4000
	s_addc_u32 s21, s19, 0
	s_cmpk_eq_i32 s26, 0x54
	s_cselect_b32 s24, s34, s20
	s_cselect_b32 s25, s35, s21
	s_cselect_b32 s22, s38, s6
	s_cselect_b32 s23, s39, s7
	s_add_u32 s20, s24, 0x8000
	s_addc_u32 s21, s25, 0
	s_add_i32 s27, 0, 0x10000
	s_add_i32 s45, 0, 0x14000
	v_add_u32_e32 v144, s27, v180
	v_add_u32_e32 v166, s45, v180
	ds_read_b128 v[132:135], v144
	ds_read_b128 v[136:139], v144 offset:1024
	ds_read_b128 v[140:143], v144 offset:2048
	ds_read_b128 v[144:147], v144 offset:3072
	ds_read_b128 v[148:151], v166
	ds_read_b128 v[152:155], v166 offset:1024
	ds_read_b128 v[156:159], v166 offset:2048
	ds_read_b128 v[166:169], v166 offset:3072
	v_lshl_add_u64 v[178:179], s[18:19], 0, v[162:163]
	s_add_i32 m0, s79, 0xc000
	ds_read_b128 v[170:173], v188
	ds_read_b128 v[174:177], v188 offset:1024
	ds_read_b128 v[192:195], v188 offset:2048
	ds_read_b128 v[196:199], v188 offset:3072
	ds_read_b128 v[200:203], v188 offset:4096
	ds_read_b128 v[204:207], v188 offset:5120
	ds_read_b128 v[214:217], v188 offset:6144
	ds_read_b128 v[218:221], v188 offset:7168
	global_load_lds_dwordx4 v[178:179], off
	v_lshl_add_u64 v[178:179], s[18:19], 0, v[164:165]
	s_add_i32 m0, s79, 0xe000
	s_nop 0
	global_load_lds_dwordx4 v[178:179], off
	s_waitcnt vmcnt(8)
	s_waitcnt lgkmcnt(0)
	s_barrier
	s_setprio 1
	s_waitcnt lgkmcnt(0)
	v_mfma_f32_16x16x32_bf16 v[128:131], v[132:135], v[170:173], 0
	v_mfma_f32_16x16x32_bf16 v[124:127], v[140:143], v[170:173], 0
	v_mfma_f32_16x16x32_bf16 v[116:119], v[132:135], v[192:195], 0
	v_mfma_f32_16x16x32_bf16 v[112:115], v[140:143], v[192:195], 0
	v_mfma_f32_16x16x32_bf16 v[96:99], v[132:135], v[200:203], 0
	v_mfma_f32_16x16x32_bf16 v[92:95], v[140:143], v[200:203], 0
	v_mfma_f32_16x16x32_bf16 v[80:83], v[132:135], v[214:217], 0
	v_mfma_f32_16x16x32_bf16 v[84:87], v[140:143], v[214:217], 0
	v_mfma_f32_16x16x32_bf16 v[128:131], v[136:139], v[174:177], v[128:131]
	v_mfma_f32_16x16x32_bf16 v[124:127], v[144:147], v[174:177], v[124:127]
	v_mfma_f32_16x16x32_bf16 v[116:119], v[136:139], v[196:199], v[116:119]
	v_mfma_f32_16x16x32_bf16 v[112:115], v[144:147], v[196:199], v[112:115]
	v_mfma_f32_16x16x32_bf16 v[96:99], v[136:139], v[204:207], v[96:99]
	v_mfma_f32_16x16x32_bf16 v[92:95], v[144:147], v[204:207], v[92:95]
	v_mfma_f32_16x16x32_bf16 v[80:83], v[136:139], v[218:221], v[80:83]
	v_mfma_f32_16x16x32_bf16 v[84:87], v[144:147], v[218:221], v[84:87]
	s_setprio 0
	s_setprio 1
	v_mfma_f32_16x16x32_bf16 v[120:123], v[148:151], v[170:173], 0
	v_mfma_f32_16x16x32_bf16 v[108:111], v[156:159], v[170:173], 0
	v_mfma_f32_16x16x32_bf16 v[104:107], v[148:151], v[192:195], 0
	v_mfma_f32_16x16x32_bf16 v[100:103], v[156:159], v[192:195], 0
	v_mfma_f32_16x16x32_bf16 v[88:91], v[148:151], v[200:203], 0
	v_mfma_f32_16x16x32_bf16 v[72:75], v[156:159], v[200:203], 0
	v_mfma_f32_16x16x32_bf16 v[68:71], v[148:151], v[214:217], 0
	v_mfma_f32_16x16x32_bf16 v[64:67], v[156:159], v[214:217], 0
	v_mfma_f32_16x16x32_bf16 v[120:123], v[152:155], v[174:177], v[120:123]
	v_mfma_f32_16x16x32_bf16 v[108:111], v[166:169], v[174:177], v[108:111]
	v_mfma_f32_16x16x32_bf16 v[104:107], v[152:155], v[196:199], v[104:107]
	v_mfma_f32_16x16x32_bf16 v[100:103], v[166:169], v[196:199], v[100:103]
	v_mfma_f32_16x16x32_bf16 v[88:91], v[152:155], v[204:207], v[88:91]
	v_mfma_f32_16x16x32_bf16 v[72:75], v[166:169], v[204:207], v[72:75]
	v_mfma_f32_16x16x32_bf16 v[68:71], v[152:155], v[218:221], v[68:71]
	v_mfma_f32_16x16x32_bf16 v[64:67], v[166:169], v[218:221], v[64:67]
	s_setprio 0
	s_barrier
	s_add_i32 s27, s27, s78
	v_lshl_add_u64 v[178:179], s[22:23], 0, v[2:3]
	s_mov_b32 m0, s27
	ds_read_b128 v[170:173], v188 offset:16384
	ds_read_b128 v[174:177], v188 offset:17408
	ds_read_b128 v[192:195], v188 offset:18432
	ds_read_b128 v[196:199], v188 offset:19456
	ds_read_b128 v[200:203], v188 offset:20480
	ds_read_b128 v[204:207], v188 offset:21504
	ds_read_b128 v[214:217], v188 offset:22528
	ds_read_b128 v[218:221], v188 offset:23552
	global_load_lds_dwordx4 v[178:179], off
	s_add_i32 m0, s27, 0x2000
	s_add_u32 s50, s22, 0x4000
	v_lshl_add_u64 v[178:179], s[22:23], 0, v[160:161]
	s_addc_u32 s51, s23, 0
	s_add_i32 s27, s45, s78
	global_load_lds_dwordx4 v[178:179], off
	v_lshl_add_u64 v[178:179], s[50:51], 0, v[2:3]
	s_mov_b32 m0, s27
	s_nop 0
	global_load_lds_dwordx4 v[178:179], off
	v_lshl_add_u64 v[178:179], s[50:51], 0, v[160:161]
	s_add_i32 m0, s27, 0x2000
	s_nop 0
	global_load_lds_dwordx4 v[178:179], off
	v_lshl_add_u64 v[178:179], s[24:25], 0, v[2:3]
	s_mov_b32 m0, s79
	s_nop 0
	global_load_lds_dwordx4 v[178:179], off
	v_lshl_add_u64 v[178:179], s[24:25], 0, v[160:161]
	s_mov_b32 m0, s40
	s_nop 0
	global_load_lds_dwordx4 v[178:179], off
	s_waitcnt vmcnt(8)
	s_waitcnt lgkmcnt(0)
	s_barrier
	s_setprio 1
	s_waitcnt lgkmcnt(0)
	v_mfma_f32_16x16x32_bf16 v[60:63], v[132:135], v[170:173], 0
	v_mfma_f32_16x16x32_bf16 v[56:59], v[140:143], v[170:173], 0
	v_mfma_f32_16x16x32_bf16 v[44:47], v[132:135], v[192:195], 0
	v_mfma_f32_16x16x32_bf16 v[48:51], v[140:143], v[192:195], 0
	v_mfma_f32_16x16x32_bf16 v[28:31], v[132:135], v[200:203], 0
	v_mfma_f32_16x16x32_bf16 v[24:27], v[140:143], v[200:203], 0
	v_mfma_f32_16x16x32_bf16 v[76:79], v[132:135], v[214:217], 0
	v_mfma_f32_16x16x32_bf16 v[16:19], v[140:143], v[214:217], 0
	v_mfma_f32_16x16x32_bf16 v[60:63], v[136:139], v[174:177], v[60:63]
	v_mfma_f32_16x16x32_bf16 v[56:59], v[144:147], v[174:177], v[56:59]
	v_mfma_f32_16x16x32_bf16 v[44:47], v[136:139], v[196:199], v[44:47]
	v_mfma_f32_16x16x32_bf16 v[48:51], v[144:147], v[196:199], v[48:51]
	v_mfma_f32_16x16x32_bf16 v[28:31], v[136:139], v[204:207], v[28:31]
	v_mfma_f32_16x16x32_bf16 v[24:27], v[144:147], v[204:207], v[24:27]
	v_mfma_f32_16x16x32_bf16 v[76:79], v[136:139], v[218:221], v[76:79]
	v_mfma_f32_16x16x32_bf16 v[16:19], v[144:147], v[218:221], v[16:19]
	s_setprio 0
	s_setprio 1
	v_mfma_f32_16x16x32_bf16 v[52:55], v[148:151], v[170:173], 0
	v_mfma_f32_16x16x32_bf16 v[40:43], v[156:159], v[170:173], 0
	v_mfma_f32_16x16x32_bf16 v[36:39], v[148:151], v[192:195], 0
	v_mfma_f32_16x16x32_bf16 v[32:35], v[156:159], v[192:195], 0
	v_mfma_f32_16x16x32_bf16 v[20:23], v[148:151], v[200:203], 0
	v_mfma_f32_16x16x32_bf16 v[12:15], v[156:159], v[200:203], 0
	v_mfma_f32_16x16x32_bf16 v[4:7], v[148:151], v[214:217], 0
	v_mfma_f32_16x16x32_bf16 v[8:11], v[156:159], v[214:217], 0
	v_mfma_f32_16x16x32_bf16 v[52:55], v[152:155], v[174:177], v[52:55]
	v_mfma_f32_16x16x32_bf16 v[40:43], v[166:169], v[174:177], v[40:43]
	v_mfma_f32_16x16x32_bf16 v[36:39], v[152:155], v[196:199], v[36:39]
	v_mfma_f32_16x16x32_bf16 v[32:35], v[166:169], v[196:199], v[32:35]
	v_mfma_f32_16x16x32_bf16 v[20:23], v[152:155], v[204:207], v[20:23]
	v_mfma_f32_16x16x32_bf16 v[12:15], v[166:169], v[204:207], v[12:15]
	v_mfma_f32_16x16x32_bf16 v[4:7], v[152:155], v[218:221], v[4:7]
	v_mfma_f32_16x16x32_bf16 v[8:11], v[166:169], v[218:221], v[8:11]
	s_setprio 0
	s_barrier
	s_add_i32 s27, 0, 0x18000
	s_add_i32 s45, 0, 0x1c000
	v_add_u32_e32 v144, s27, v180
	v_add_u32_e32 v166, s45, v180
	ds_read_b128 v[132:135], v144
	ds_read_b128 v[136:139], v144 offset:1024
	ds_read_b128 v[140:143], v144 offset:2048
	ds_read_b128 v[144:147], v144 offset:3072
	ds_read_b128 v[148:151], v166
	ds_read_b128 v[152:155], v166 offset:1024
	ds_read_b128 v[156:159], v166 offset:2048
	ds_read_b128 v[166:169], v166 offset:3072
	s_add_u32 s24, s24, 0x4000
	s_addc_u32 s25, s25, 0
	s_mov_b32 m0, s41
	v_lshl_add_u64 v[178:179], s[24:25], 0, v[2:3]
	ds_read_b128 v[170:173], v188 offset:32768
	ds_read_b128 v[174:177], v188 offset:33792
	ds_read_b128 v[192:195], v188 offset:34816
	ds_read_b128 v[196:199], v188 offset:35840
	ds_read_b128 v[200:203], v188 offset:36864
	ds_read_b128 v[204:207], v188 offset:37888
	ds_read_b128 v[214:217], v188 offset:38912
	ds_read_b128 v[218:221], v188 offset:39936
	global_load_lds_dwordx4 v[178:179], off
	v_lshl_add_u64 v[178:179], s[24:25], 0, v[160:161]
	s_mov_b32 m0, s46
	s_nop 0
	global_load_lds_dwordx4 v[178:179], off
	s_waitcnt vmcnt(8)
	s_waitcnt lgkmcnt(0)
	s_barrier
	s_setprio 1
	s_waitcnt lgkmcnt(0)
	v_mfma_f32_16x16x32_bf16 v[128:131], v[132:135], v[170:173], v[128:131]
	v_mfma_f32_16x16x32_bf16 v[124:127], v[140:143], v[170:173], v[124:127]
	v_mfma_f32_16x16x32_bf16 v[116:119], v[132:135], v[192:195], v[116:119]
	v_mfma_f32_16x16x32_bf16 v[112:115], v[140:143], v[192:195], v[112:115]
	v_mfma_f32_16x16x32_bf16 v[96:99], v[132:135], v[200:203], v[96:99]
	v_mfma_f32_16x16x32_bf16 v[92:95], v[140:143], v[200:203], v[92:95]
	v_mfma_f32_16x16x32_bf16 v[80:83], v[132:135], v[214:217], v[80:83]
	v_mfma_f32_16x16x32_bf16 v[84:87], v[140:143], v[214:217], v[84:87]
	v_mfma_f32_16x16x32_bf16 v[128:131], v[136:139], v[174:177], v[128:131]
	v_mfma_f32_16x16x32_bf16 v[124:127], v[144:147], v[174:177], v[124:127]
	v_mfma_f32_16x16x32_bf16 v[116:119], v[136:139], v[196:199], v[116:119]
	v_mfma_f32_16x16x32_bf16 v[112:115], v[144:147], v[196:199], v[112:115]
	v_mfma_f32_16x16x32_bf16 v[96:99], v[136:139], v[204:207], v[96:99]
	v_mfma_f32_16x16x32_bf16 v[92:95], v[144:147], v[204:207], v[92:95]
	v_mfma_f32_16x16x32_bf16 v[80:83], v[136:139], v[218:221], v[80:83]
	v_mfma_f32_16x16x32_bf16 v[84:87], v[144:147], v[218:221], v[84:87]
	s_setprio 0
	s_setprio 1
	v_mfma_f32_16x16x32_bf16 v[120:123], v[148:151], v[170:173], v[120:123]
	v_mfma_f32_16x16x32_bf16 v[108:111], v[156:159], v[170:173], v[108:111]
	v_mfma_f32_16x16x32_bf16 v[104:107], v[148:151], v[192:195], v[104:107]
	v_mfma_f32_16x16x32_bf16 v[100:103], v[156:159], v[192:195], v[100:103]
	v_mfma_f32_16x16x32_bf16 v[88:91], v[148:151], v[200:203], v[88:91]
	v_mfma_f32_16x16x32_bf16 v[72:75], v[156:159], v[200:203], v[72:75]
	v_mfma_f32_16x16x32_bf16 v[68:71], v[148:151], v[214:217], v[68:71]
	v_mfma_f32_16x16x32_bf16 v[64:67], v[156:159], v[214:217], v[64:67]
	v_mfma_f32_16x16x32_bf16 v[120:123], v[152:155], v[174:177], v[120:123]
	v_mfma_f32_16x16x32_bf16 v[108:111], v[166:169], v[174:177], v[108:111]
	v_mfma_f32_16x16x32_bf16 v[104:107], v[152:155], v[196:199], v[104:107]
	v_mfma_f32_16x16x32_bf16 v[100:103], v[166:169], v[196:199], v[100:103]
	v_mfma_f32_16x16x32_bf16 v[88:91], v[152:155], v[204:207], v[88:91]
	v_mfma_f32_16x16x32_bf16 v[72:75], v[166:169], v[204:207], v[72:75]
	v_mfma_f32_16x16x32_bf16 v[68:71], v[152:155], v[218:221], v[68:71]
	v_mfma_f32_16x16x32_bf16 v[64:67], v[166:169], v[218:221], v[64:67]
	s_setprio 0
	s_barrier
	s_add_u32 s24, s22, 0x8000
	s_addc_u32 s25, s23, 0
	s_add_i32 s27, s27, s78
	v_lshl_add_u64 v[178:179], s[24:25], 0, v[2:3]
	s_mov_b32 m0, s27
	ds_read_b128 v[170:173], v188 offset:49152
	ds_read_b128 v[174:177], v188 offset:50176
	ds_read_b128 v[192:195], v188 offset:51200
	ds_read_b128 v[196:199], v188 offset:52224
	ds_read_b128 v[200:203], v188 offset:53248
	ds_read_b128 v[204:207], v188 offset:54272
	ds_read_b128 v[214:217], v188 offset:55296
	ds_read_b128 v[218:221], v188 offset:56320
	global_load_lds_dwordx4 v[178:179], off
	s_add_i32 m0, s27, 0x2000
	s_add_u32 s22, s22, 0xc000
	v_lshl_add_u64 v[178:179], s[24:25], 0, v[160:161]
	s_addc_u32 s23, s23, 0
	s_add_i32 s24, s45, s78
	global_load_lds_dwordx4 v[178:179], off
	v_lshl_add_u64 v[178:179], s[22:23], 0, v[2:3]
	s_mov_b32 m0, s24
	s_nop 0
	global_load_lds_dwordx4 v[178:179], off
	v_lshl_add_u64 v[178:179], s[22:23], 0, v[160:161]
	s_add_i32 m0, s24, 0x2000
	s_nop 0
	global_load_lds_dwordx4 v[178:179], off
	v_lshl_add_u64 v[178:179], s[20:21], 0, v[2:3]
	s_mov_b32 m0, s52
	s_nop 0
	global_load_lds_dwordx4 v[178:179], off
	v_lshl_add_u64 v[178:179], s[20:21], 0, v[160:161]
	s_mov_b32 m0, s53
	s_nop 0
	global_load_lds_dwordx4 v[178:179], off
	s_waitcnt vmcnt(8)
	s_waitcnt lgkmcnt(0)
	s_barrier
	s_setprio 1
	s_waitcnt lgkmcnt(0)
	v_mfma_f32_16x16x32_bf16 v[60:63], v[132:135], v[170:173], v[60:63]
	v_mfma_f32_16x16x32_bf16 v[56:59], v[140:143], v[170:173], v[56:59]
	v_mfma_f32_16x16x32_bf16 v[44:47], v[132:135], v[192:195], v[44:47]
	v_mfma_f32_16x16x32_bf16 v[48:51], v[140:143], v[192:195], v[48:51]
	v_mfma_f32_16x16x32_bf16 v[28:31], v[132:135], v[200:203], v[28:31]
	v_mfma_f32_16x16x32_bf16 v[24:27], v[140:143], v[200:203], v[24:27]
	v_mfma_f32_16x16x32_bf16 v[76:79], v[132:135], v[214:217], v[76:79]
	v_mfma_f32_16x16x32_bf16 v[16:19], v[140:143], v[214:217], v[16:19]
	v_mfma_f32_16x16x32_bf16 v[60:63], v[136:139], v[174:177], v[60:63]
	v_mfma_f32_16x16x32_bf16 v[56:59], v[144:147], v[174:177], v[56:59]
	v_mfma_f32_16x16x32_bf16 v[44:47], v[136:139], v[196:199], v[44:47]
	v_mfma_f32_16x16x32_bf16 v[48:51], v[144:147], v[196:199], v[48:51]
	v_mfma_f32_16x16x32_bf16 v[28:31], v[136:139], v[204:207], v[28:31]
	v_mfma_f32_16x16x32_bf16 v[24:27], v[144:147], v[204:207], v[24:27]
	v_mfma_f32_16x16x32_bf16 v[76:79], v[136:139], v[218:221], v[76:79]
	v_mfma_f32_16x16x32_bf16 v[16:19], v[144:147], v[218:221], v[16:19]
	s_setprio 0
	s_setprio 1
	v_mfma_f32_16x16x32_bf16 v[52:55], v[148:151], v[170:173], v[52:55]
	v_mfma_f32_16x16x32_bf16 v[40:43], v[156:159], v[170:173], v[40:43]
	v_mfma_f32_16x16x32_bf16 v[36:39], v[148:151], v[192:195], v[36:39]
	v_mfma_f32_16x16x32_bf16 v[32:35], v[156:159], v[192:195], v[32:35]
	v_mfma_f32_16x16x32_bf16 v[20:23], v[148:151], v[200:203], v[20:23]
	v_mfma_f32_16x16x32_bf16 v[12:15], v[156:159], v[200:203], v[12:15]
	v_mfma_f32_16x16x32_bf16 v[4:7], v[148:151], v[214:217], v[4:7]
	v_mfma_f32_16x16x32_bf16 v[8:11], v[156:159], v[214:217], v[8:11]
	v_mfma_f32_16x16x32_bf16 v[52:55], v[152:155], v[174:177], v[52:55]
	v_mfma_f32_16x16x32_bf16 v[40:43], v[166:169], v[174:177], v[40:43]
	v_mfma_f32_16x16x32_bf16 v[36:39], v[152:155], v[196:199], v[36:39]
	v_mfma_f32_16x16x32_bf16 v[32:35], v[166:169], v[196:199], v[32:35]
	v_mfma_f32_16x16x32_bf16 v[20:23], v[152:155], v[204:207], v[20:23]
	v_mfma_f32_16x16x32_bf16 v[12:15], v[166:169], v[204:207], v[12:15]
	v_mfma_f32_16x16x32_bf16 v[4:7], v[152:155], v[218:221], v[4:7]
	v_mfma_f32_16x16x32_bf16 v[8:11], v[166:169], v[218:221], v[8:11]
	s_setprio 0
	s_barrier
	s_add_i32 s26, s26, 2
	s_add_u32 s18, s18, 0x10000
	s_addc_u32 s19, s19, 0
	s_add_u32 s6, s6, 0x10000
	s_addc_u32 s7, s7, 0
	s_cmpk_gt_u32 s26, 0x55
	.p2align	6
